# v111: v106 with write-through (sc1) stores for the transposed tile outputs of the transposing norm and the gMLP transpose (consumed as GEMM operands on other XCDs after the barrier)
# speedup vs baseline: 1.0140x; 1.0010x over previous
.LBB0_119:
	s_ashr_i32 s7, s6, 31
	s_lshl_b64 s[8:9], s[6:7], 11
	v_lshl_add_u64 v[8:9], v[6:7], 0, s[8:9]
	s_mov_b64 s[8:9], 0
	v_mov_b32_e32 v10, v50
	v_readlane_b32 s9, v254, 63
	s_mul_i32 s9, s9, 64
	v_add_u32_e32 v10, s9, v10
	v_add_co_u32_e32 v80, vcc, 0xe800000, v8
	s_nop 1
	v_addc_co_u32_e32 v81, vcc, 0, v9, vcc
	global_load_dwordx2 v[84:85], v[80:81], off
	global_load_dwordx2 v[86:87], v[80:81], off offset:512
	global_load_dwordx2 v[88:89], v[80:81], off offset:1024
	global_load_dwordx2 v[90:91], v[80:81], off offset:1536
	global_load_dwordx2 v[92:93], v[80:81], off offset:2048
	global_load_dwordx2 v[94:95], v[80:81], off offset:2560
	global_load_dwordx2 v[96:97], v[80:81], off offset:3072
	global_load_dwordx2 v[98:99], v[80:81], off offset:3584
	v_add_co_u32_e32 v80, vcc, 0x1000, v80
	s_nop 1
	v_addc_co_u32_e32 v81, vcc, 0, v81, vcc
	global_load_dwordx2 v[100:101], v[80:81], off
	global_load_dwordx2 v[102:103], v[80:81], off offset:512
	global_load_dwordx2 v[104:105], v[80:81], off offset:1024
	global_load_dwordx2 v[106:107], v[80:81], off offset:1536
	global_load_dwordx2 v[108:109], v[80:81], off offset:2048
	global_load_dwordx2 v[110:111], v[80:81], off offset:2560
	global_load_dwordx2 v[112:113], v[80:81], off offset:3072
	global_load_dwordx2 v[114:115], v[80:81], off offset:3584
	v_add_co_u32_e32 v80, vcc, 0x1000, v80
	s_nop 1
	v_addc_co_u32_e32 v81, vcc, 0, v81, vcc
	global_load_dwordx2 v[116:117], v[80:81], off
	global_load_dwordx2 v[118:119], v[80:81], off offset:512
	global_load_dwordx2 v[120:121], v[80:81], off offset:1024
	global_load_dwordx2 v[122:123], v[80:81], off offset:1536
	global_load_dwordx2 v[124:125], v[80:81], off offset:2048
	global_load_dwordx2 v[126:127], v[80:81], off offset:2560
	global_load_dwordx2 v[128:129], v[80:81], off offset:3072
	global_load_dwordx2 v[130:131], v[80:81], off offset:3584
	v_add_co_u32_e32 v80, vcc, 0x1000, v80
	s_nop 1
	v_addc_co_u32_e32 v81, vcc, 0, v81, vcc
	global_load_dwordx2 v[132:133], v[80:81], off
	global_load_dwordx2 v[134:135], v[80:81], off offset:512
	global_load_dwordx2 v[136:137], v[80:81], off offset:1024
	global_load_dwordx2 v[138:139], v[80:81], off offset:1536
	global_load_dwordx2 v[140:141], v[80:81], off offset:2048
	global_load_dwordx2 v[142:143], v[80:81], off offset:2560
	global_load_dwordx2 v[144:145], v[80:81], off offset:3072
	global_load_dwordx2 v[146:147], v[80:81], off offset:3584
	s_mov_b32 s8, 0x3a800000
	s_waitcnt vmcnt(28)
	v_lshlrev_b32_e32 v82, 16, v84
	v_and_b32_e32 v83, 0xffff0000, v84
	v_mul_f32_e32 v148, v82, v82
	v_fmac_f32_e32 v148, v83, v83
	v_lshlrev_b32_e32 v82, 16, v85
	v_and_b32_e32 v83, 0xffff0000, v85
	v_fmac_f32_e32 v148, v82, v82
	v_fmac_f32_e32 v148, v83, v83
	v_lshlrev_b32_e32 v82, 16, v86
	v_and_b32_e32 v83, 0xffff0000, v86
	v_fmac_f32_e32 v148, v82, v82
	v_fmac_f32_e32 v148, v83, v83
	v_lshlrev_b32_e32 v82, 16, v87
	v_and_b32_e32 v83, 0xffff0000, v87
	v_fmac_f32_e32 v148, v82, v82
	v_fmac_f32_e32 v148, v83, v83
	v_lshlrev_b32_e32 v82, 16, v88
	v_and_b32_e32 v83, 0xffff0000, v88
	v_fmac_f32_e32 v148, v82, v82
	v_fmac_f32_e32 v148, v83, v83
	v_lshlrev_b32_e32 v82, 16, v89
	v_and_b32_e32 v83, 0xffff0000, v89
	v_fmac_f32_e32 v148, v82, v82
	v_fmac_f32_e32 v148, v83, v83
	v_lshlrev_b32_e32 v82, 16, v90
	v_and_b32_e32 v83, 0xffff0000, v90
	v_fmac_f32_e32 v148, v82, v82
	v_fmac_f32_e32 v148, v83, v83
	v_lshlrev_b32_e32 v82, 16, v91
	v_and_b32_e32 v83, 0xffff0000, v91
	v_fmac_f32_e32 v148, v82, v82
	v_fmac_f32_e32 v148, v83, v83
	s_waitcnt vmcnt(24)
	v_lshlrev_b32_e32 v82, 16, v92
	v_and_b32_e32 v83, 0xffff0000, v92
	v_mul_f32_e32 v149, v82, v82
	v_fmac_f32_e32 v149, v83, v83
	v_lshlrev_b32_e32 v82, 16, v93
	v_and_b32_e32 v83, 0xffff0000, v93
	v_fmac_f32_e32 v149, v82, v82
	v_fmac_f32_e32 v149, v83, v83
	v_lshlrev_b32_e32 v82, 16, v94
	v_and_b32_e32 v83, 0xffff0000, v94
	v_fmac_f32_e32 v149, v82, v82
	v_fmac_f32_e32 v149, v83, v83
	v_lshlrev_b32_e32 v82, 16, v95
	v_and_b32_e32 v83, 0xffff0000, v95
	v_fmac_f32_e32 v149, v82, v82
	v_fmac_f32_e32 v149, v83, v83
	v_lshlrev_b32_e32 v82, 16, v96
	v_and_b32_e32 v83, 0xffff0000, v96
	v_fmac_f32_e32 v149, v82, v82
	v_fmac_f32_e32 v149, v83, v83
	v_lshlrev_b32_e32 v82, 16, v97
	v_and_b32_e32 v83, 0xffff0000, v97
	v_fmac_f32_e32 v149, v82, v82
	v_fmac_f32_e32 v149, v83, v83
	v_lshlrev_b32_e32 v82, 16, v98
	v_and_b32_e32 v83, 0xffff0000, v98
	v_fmac_f32_e32 v149, v82, v82
	v_fmac_f32_e32 v149, v83, v83
	v_lshlrev_b32_e32 v82, 16, v99
	v_and_b32_e32 v83, 0xffff0000, v99
	v_fmac_f32_e32 v149, v82, v82
	v_fmac_f32_e32 v149, v83, v83
	s_waitcnt vmcnt(20)
	v_lshlrev_b32_e32 v82, 16, v100
	v_and_b32_e32 v83, 0xffff0000, v100
	v_mul_f32_e32 v150, v82, v82
	v_fmac_f32_e32 v150, v83, v83
	v_lshlrev_b32_e32 v82, 16, v101
	v_and_b32_e32 v83, 0xffff0000, v101
	v_fmac_f32_e32 v150, v82, v82
	v_fmac_f32_e32 v150, v83, v83
	v_lshlrev_b32_e32 v82, 16, v102
	v_and_b32_e32 v83, 0xffff0000, v102
	v_fmac_f32_e32 v150, v82, v82
	v_fmac_f32_e32 v150, v83, v83
	v_lshlrev_b32_e32 v82, 16, v103
	v_and_b32_e32 v83, 0xffff0000, v103
	v_fmac_f32_e32 v150, v82, v82
	v_fmac_f32_e32 v150, v83, v83
	v_lshlrev_b32_e32 v82, 16, v104
	v_and_b32_e32 v83, 0xffff0000, v104
	v_fmac_f32_e32 v150, v82, v82
	v_fmac_f32_e32 v150, v83, v83
	v_lshlrev_b32_e32 v82, 16, v105
	v_and_b32_e32 v83, 0xffff0000, v105
	v_fmac_f32_e32 v150, v82, v82
	v_fmac_f32_e32 v150, v83, v83
	v_lshlrev_b32_e32 v82, 16, v106
	v_and_b32_e32 v83, 0xffff0000, v106
	v_fmac_f32_e32 v150, v82, v82
	v_fmac_f32_e32 v150, v83, v83
	v_lshlrev_b32_e32 v82, 16, v107
	v_and_b32_e32 v83, 0xffff0000, v107
	v_fmac_f32_e32 v150, v82, v82
	v_fmac_f32_e32 v150, v83, v83
	s_waitcnt vmcnt(16)
	v_lshlrev_b32_e32 v82, 16, v108
	v_and_b32_e32 v83, 0xffff0000, v108
	v_mul_f32_e32 v151, v82, v82
	v_fmac_f32_e32 v151, v83, v83
	v_lshlrev_b32_e32 v82, 16, v109
	v_and_b32_e32 v83, 0xffff0000, v109
	v_fmac_f32_e32 v151, v82, v82
	v_fmac_f32_e32 v151, v83, v83
	v_lshlrev_b32_e32 v82, 16, v110
	v_and_b32_e32 v83, 0xffff0000, v110
	v_fmac_f32_e32 v151, v82, v82
	v_fmac_f32_e32 v151, v83, v83
	v_lshlrev_b32_e32 v82, 16, v111
	v_and_b32_e32 v83, 0xffff0000, v111
	v_fmac_f32_e32 v151, v82, v82
	v_fmac_f32_e32 v151, v83, v83
	v_lshlrev_b32_e32 v82, 16, v112
	v_and_b32_e32 v83, 0xffff0000, v112
	v_fmac_f32_e32 v151, v82, v82
	v_fmac_f32_e32 v151, v83, v83
	v_lshlrev_b32_e32 v82, 16, v113
	v_and_b32_e32 v83, 0xffff0000, v113
	v_fmac_f32_e32 v151, v82, v82
	v_fmac_f32_e32 v151, v83, v83
	v_lshlrev_b32_e32 v82, 16, v114
	v_and_b32_e32 v83, 0xffff0000, v114
	v_fmac_f32_e32 v151, v82, v82
	v_fmac_f32_e32 v151, v83, v83
	v_lshlrev_b32_e32 v82, 16, v115
	v_and_b32_e32 v83, 0xffff0000, v115
	v_fmac_f32_e32 v151, v82, v82
	v_fmac_f32_e32 v151, v83, v83
	s_waitcnt vmcnt(12)
	v_lshlrev_b32_e32 v82, 16, v116
	v_and_b32_e32 v83, 0xffff0000, v116
	v_mul_f32_e32 v152, v82, v82
	v_fmac_f32_e32 v152, v83, v83
	v_lshlrev_b32_e32 v82, 16, v117
	v_and_b32_e32 v83, 0xffff0000, v117
	v_fmac_f32_e32 v152, v82, v82
	v_fmac_f32_e32 v152, v83, v83
	v_lshlrev_b32_e32 v82, 16, v118
	v_and_b32_e32 v83, 0xffff0000, v118
	v_fmac_f32_e32 v152, v82, v82
	v_fmac_f32_e32 v152, v83, v83
	v_lshlrev_b32_e32 v82, 16, v119
	v_and_b32_e32 v83, 0xffff0000, v119
	v_fmac_f32_e32 v152, v82, v82
	v_fmac_f32_e32 v152, v83, v83
	v_lshlrev_b32_e32 v82, 16, v120
	v_and_b32_e32 v83, 0xffff0000, v120
	v_fmac_f32_e32 v152, v82, v82
	v_fmac_f32_e32 v152, v83, v83
	v_lshlrev_b32_e32 v82, 16, v121
	v_and_b32_e32 v83, 0xffff0000, v121
	v_fmac_f32_e32 v152, v82, v82
	v_fmac_f32_e32 v152, v83, v83
	v_lshlrev_b32_e32 v82, 16, v122
	v_and_b32_e32 v83, 0xffff0000, v122
	v_fmac_f32_e32 v152, v82, v82
	v_fmac_f32_e32 v152, v83, v83
	v_lshlrev_b32_e32 v82, 16, v123
	v_and_b32_e32 v83, 0xffff0000, v123
	v_fmac_f32_e32 v152, v82, v82
	v_fmac_f32_e32 v152, v83, v83
	s_waitcnt vmcnt(8)
	v_lshlrev_b32_e32 v82, 16, v124
	v_and_b32_e32 v83, 0xffff0000, v124
	v_mul_f32_e32 v153, v82, v82
	v_fmac_f32_e32 v153, v83, v83
	v_lshlrev_b32_e32 v82, 16, v125
	v_and_b32_e32 v83, 0xffff0000, v125
	v_fmac_f32_e32 v153, v82, v82
	v_fmac_f32_e32 v153, v83, v83
	v_lshlrev_b32_e32 v82, 16, v126
	v_and_b32_e32 v83, 0xffff0000, v126
	v_fmac_f32_e32 v153, v82, v82
	v_fmac_f32_e32 v153, v83, v83
	v_lshlrev_b32_e32 v82, 16, v127
	v_and_b32_e32 v83, 0xffff0000, v127
	v_fmac_f32_e32 v153, v82, v82
	v_fmac_f32_e32 v153, v83, v83
	v_lshlrev_b32_e32 v82, 16, v128
	v_and_b32_e32 v83, 0xffff0000, v128
	v_fmac_f32_e32 v153, v82, v82
	v_fmac_f32_e32 v153, v83, v83
	v_lshlrev_b32_e32 v82, 16, v129
	v_and_b32_e32 v83, 0xffff0000, v129
	v_fmac_f32_e32 v153, v82, v82
	v_fmac_f32_e32 v153, v83, v83
	v_lshlrev_b32_e32 v82, 16, v130
	v_and_b32_e32 v83, 0xffff0000, v130
	v_fmac_f32_e32 v153, v82, v82
	v_fmac_f32_e32 v153, v83, v83
	v_lshlrev_b32_e32 v82, 16, v131
	v_and_b32_e32 v83, 0xffff0000, v131
	v_fmac_f32_e32 v153, v82, v82
	v_fmac_f32_e32 v153, v83, v83
	s_waitcnt vmcnt(4)
	v_lshlrev_b32_e32 v82, 16, v132
	v_and_b32_e32 v83, 0xffff0000, v132
	v_mul_f32_e32 v154, v82, v82
	v_fmac_f32_e32 v154, v83, v83
	v_lshlrev_b32_e32 v82, 16, v133
	v_and_b32_e32 v83, 0xffff0000, v133
	v_fmac_f32_e32 v154, v82, v82
	v_fmac_f32_e32 v154, v83, v83
	v_lshlrev_b32_e32 v82, 16, v134
	v_and_b32_e32 v83, 0xffff0000, v134
	v_fmac_f32_e32 v154, v82, v82
	v_fmac_f32_e32 v154, v83, v83
	v_lshlrev_b32_e32 v82, 16, v135
	v_and_b32_e32 v83, 0xffff0000, v135
	v_fmac_f32_e32 v154, v82, v82
	v_fmac_f32_e32 v154, v83, v83
	v_lshlrev_b32_e32 v82, 16, v136
	v_and_b32_e32 v83, 0xffff0000, v136
	v_fmac_f32_e32 v154, v82, v82
	v_fmac_f32_e32 v154, v83, v83
	v_lshlrev_b32_e32 v82, 16, v137
	v_and_b32_e32 v83, 0xffff0000, v137
	v_fmac_f32_e32 v154, v82, v82
	v_fmac_f32_e32 v154, v83, v83
	v_lshlrev_b32_e32 v82, 16, v138
	v_and_b32_e32 v83, 0xffff0000, v138
	v_fmac_f32_e32 v154, v82, v82
	v_fmac_f32_e32 v154, v83, v83
	v_lshlrev_b32_e32 v82, 16, v139
	v_and_b32_e32 v83, 0xffff0000, v139
	v_fmac_f32_e32 v154, v82, v82
	v_fmac_f32_e32 v154, v83, v83
	s_waitcnt vmcnt(0)
	v_lshlrev_b32_e32 v82, 16, v140
	v_and_b32_e32 v83, 0xffff0000, v140
	v_mul_f32_e32 v155, v82, v82
	v_fmac_f32_e32 v155, v83, v83
	v_lshlrev_b32_e32 v82, 16, v141
	v_and_b32_e32 v83, 0xffff0000, v141
	v_fmac_f32_e32 v155, v82, v82
	v_fmac_f32_e32 v155, v83, v83
	v_lshlrev_b32_e32 v82, 16, v142
	v_and_b32_e32 v83, 0xffff0000, v142
	v_fmac_f32_e32 v155, v82, v82
	v_fmac_f32_e32 v155, v83, v83
	v_lshlrev_b32_e32 v82, 16, v143
	v_and_b32_e32 v83, 0xffff0000, v143
	v_fmac_f32_e32 v155, v82, v82
	v_fmac_f32_e32 v155, v83, v83
	v_lshlrev_b32_e32 v82, 16, v144
	v_and_b32_e32 v83, 0xffff0000, v144
	v_fmac_f32_e32 v155, v82, v82
	v_fmac_f32_e32 v155, v83, v83
	v_lshlrev_b32_e32 v82, 16, v145
	v_and_b32_e32 v83, 0xffff0000, v145
	v_fmac_f32_e32 v155, v82, v82
	v_fmac_f32_e32 v155, v83, v83
	v_lshlrev_b32_e32 v82, 16, v146
	v_and_b32_e32 v83, 0xffff0000, v146
	v_fmac_f32_e32 v155, v82, v82
	v_fmac_f32_e32 v155, v83, v83
	v_lshlrev_b32_e32 v82, 16, v147
	v_and_b32_e32 v83, 0xffff0000, v147
	v_fmac_f32_e32 v155, v82, v82
	v_fmac_f32_e32 v155, v83, v83
	s_nop 1
	v_add_f32_dpp v148, v148, v148 row_ror:8 row_mask:0xf bank_mask:0xf
	v_add_f32_dpp v149, v149, v149 row_ror:8 row_mask:0xf bank_mask:0xf
	v_add_f32_dpp v150, v150, v150 row_ror:8 row_mask:0xf bank_mask:0xf
	v_add_f32_dpp v151, v151, v151 row_ror:8 row_mask:0xf bank_mask:0xf
	v_add_f32_dpp v152, v152, v152 row_ror:8 row_mask:0xf bank_mask:0xf
	v_add_f32_dpp v153, v153, v153 row_ror:8 row_mask:0xf bank_mask:0xf
	v_add_f32_dpp v154, v154, v154 row_ror:8 row_mask:0xf bank_mask:0xf
	v_add_f32_dpp v155, v155, v155 row_ror:8 row_mask:0xf bank_mask:0xf
	v_add_f32_dpp v148, v148, v148 row_ror:4 row_mask:0xf bank_mask:0xf
	v_add_f32_dpp v149, v149, v149 row_ror:4 row_mask:0xf bank_mask:0xf
	v_add_f32_dpp v150, v150, v150 row_ror:4 row_mask:0xf bank_mask:0xf
	v_add_f32_dpp v151, v151, v151 row_ror:4 row_mask:0xf bank_mask:0xf
	v_add_f32_dpp v152, v152, v152 row_ror:4 row_mask:0xf bank_mask:0xf
	v_add_f32_dpp v153, v153, v153 row_ror:4 row_mask:0xf bank_mask:0xf
	v_add_f32_dpp v154, v154, v154 row_ror:4 row_mask:0xf bank_mask:0xf
	v_add_f32_dpp v155, v155, v155 row_ror:4 row_mask:0xf bank_mask:0xf
	v_add_f32_dpp v148, v148, v148 row_ror:2 row_mask:0xf bank_mask:0xf
	v_add_f32_dpp v149, v149, v149 row_ror:2 row_mask:0xf bank_mask:0xf
	v_add_f32_dpp v150, v150, v150 row_ror:2 row_mask:0xf bank_mask:0xf
	v_add_f32_dpp v151, v151, v151 row_ror:2 row_mask:0xf bank_mask:0xf
	v_add_f32_dpp v152, v152, v152 row_ror:2 row_mask:0xf bank_mask:0xf
	v_add_f32_dpp v153, v153, v153 row_ror:2 row_mask:0xf bank_mask:0xf
	v_add_f32_dpp v154, v154, v154 row_ror:2 row_mask:0xf bank_mask:0xf
	v_add_f32_dpp v155, v155, v155 row_ror:2 row_mask:0xf bank_mask:0xf
	v_add_f32_dpp v148, v148, v148 row_ror:1 row_mask:0xf bank_mask:0xf
	v_add_f32_dpp v149, v149, v149 row_ror:1 row_mask:0xf bank_mask:0xf
	v_add_f32_dpp v150, v150, v150 row_ror:1 row_mask:0xf bank_mask:0xf
	v_add_f32_dpp v151, v151, v151 row_ror:1 row_mask:0xf bank_mask:0xf
	v_add_f32_dpp v152, v152, v152 row_ror:1 row_mask:0xf bank_mask:0xf
	v_add_f32_dpp v153, v153, v153 row_ror:1 row_mask:0xf bank_mask:0xf
	v_add_f32_dpp v154, v154, v154 row_ror:1 row_mask:0xf bank_mask:0xf
	v_add_f32_dpp v155, v155, v155 row_ror:1 row_mask:0xf bank_mask:0xf
	v_mov_b32_e32 v156, v148
	v_mov_b32_e32 v157, v149
	v_mov_b32_e32 v158, v150
	v_mov_b32_e32 v159, v151
	v_mov_b32_e32 v160, v152
	v_mov_b32_e32 v161, v153
	v_mov_b32_e32 v162, v154
	v_mov_b32_e32 v163, v155
	s_nop 1
	v_permlane16_swap_b32_e32 v156, v148
	v_permlane16_swap_b32_e32 v157, v149
	v_permlane16_swap_b32_e32 v158, v150
	v_permlane16_swap_b32_e32 v159, v151
	v_permlane16_swap_b32_e32 v160, v152
	v_permlane16_swap_b32_e32 v161, v153
	v_permlane16_swap_b32_e32 v162, v154
	v_permlane16_swap_b32_e32 v163, v155
	v_add_f32_e32 v148, v148, v156
	v_add_f32_e32 v149, v149, v157
	v_add_f32_e32 v150, v150, v158
	v_add_f32_e32 v151, v151, v159
	v_add_f32_e32 v152, v152, v160
	v_add_f32_e32 v153, v153, v161
	v_add_f32_e32 v154, v154, v162
	v_add_f32_e32 v155, v155, v163
	v_mov_b32_e32 v156, v148
	v_mov_b32_e32 v157, v149
	v_mov_b32_e32 v158, v150
	v_mov_b32_e32 v159, v151
	v_mov_b32_e32 v160, v152
	v_mov_b32_e32 v161, v153
	v_mov_b32_e32 v162, v154
	v_mov_b32_e32 v163, v155
	s_nop 1
	v_permlane32_swap_b32_e32 v156, v148
	v_permlane32_swap_b32_e32 v157, v149
	v_permlane32_swap_b32_e32 v158, v150
	v_permlane32_swap_b32_e32 v159, v151
	v_permlane32_swap_b32_e32 v160, v152
	v_permlane32_swap_b32_e32 v161, v153
	v_permlane32_swap_b32_e32 v162, v154
	v_permlane32_swap_b32_e32 v163, v155
	v_add_f32_e32 v148, v148, v156
	v_add_f32_e32 v149, v149, v157
	v_add_f32_e32 v150, v150, v158
	v_add_f32_e32 v151, v151, v159
	v_add_f32_e32 v152, v152, v160
	v_add_f32_e32 v153, v153, v161
	v_add_f32_e32 v154, v154, v162
	v_add_f32_e32 v155, v155, v163
	v_fma_f32 v148, v148, s8, v167
	v_fma_f32 v149, v149, s8, v167
	v_fma_f32 v150, v150, s8, v167
	v_fma_f32 v151, v151, s8, v167
	v_fma_f32 v152, v152, s8, v167
	v_fma_f32 v153, v153, s8, v167
	v_fma_f32 v154, v154, s8, v167
	v_fma_f32 v155, v155, s8, v167
	v_rsq_f32_e32 v148, v148
	v_rsq_f32_e32 v149, v149
	v_rsq_f32_e32 v150, v150
	v_rsq_f32_e32 v151, v151
	v_rsq_f32_e32 v152, v152
	v_rsq_f32_e32 v153, v153
	v_rsq_f32_e32 v154, v154
	v_rsq_f32_e32 v155, v155
	s_nop 0
	v_lshlrev_b32_e32 v82, 16, v84
	v_and_b32_e32 v83, 0xffff0000, v84
	v_mul_f32_e32 v82, v82, v148
	v_mul_f32_e32 v83, v83, v148
	v_cvt_pk_bf16_f32 v84, v82, v83
	v_lshlrev_b32_e32 v82, 16, v85
	v_and_b32_e32 v83, 0xffff0000, v85
	v_mul_f32_e32 v82, v82, v148
	v_mul_f32_e32 v83, v83, v148
	v_cvt_pk_bf16_f32 v85, v82, v83
	v_lshlrev_b32_e32 v82, 16, v86
	v_and_b32_e32 v83, 0xffff0000, v86
	v_mul_f32_e32 v82, v82, v148
	v_mul_f32_e32 v83, v83, v148
	v_cvt_pk_bf16_f32 v86, v82, v83
	v_lshlrev_b32_e32 v82, 16, v87
	v_and_b32_e32 v83, 0xffff0000, v87
	v_mul_f32_e32 v82, v82, v148
	v_mul_f32_e32 v83, v83, v148
	v_cvt_pk_bf16_f32 v87, v82, v83
	v_lshlrev_b32_e32 v82, 16, v88
	v_and_b32_e32 v83, 0xffff0000, v88
	v_mul_f32_e32 v82, v82, v148
	v_mul_f32_e32 v83, v83, v148
	v_cvt_pk_bf16_f32 v88, v82, v83
	v_lshlrev_b32_e32 v82, 16, v89
	v_and_b32_e32 v83, 0xffff0000, v89
	v_mul_f32_e32 v82, v82, v148
	v_mul_f32_e32 v83, v83, v148
	v_cvt_pk_bf16_f32 v89, v82, v83
	v_lshlrev_b32_e32 v82, 16, v90
	v_and_b32_e32 v83, 0xffff0000, v90
	v_mul_f32_e32 v82, v82, v148
	v_mul_f32_e32 v83, v83, v148
	v_cvt_pk_bf16_f32 v90, v82, v83
	v_lshlrev_b32_e32 v82, 16, v91
	v_and_b32_e32 v83, 0xffff0000, v91
	v_mul_f32_e32 v82, v82, v148
	v_mul_f32_e32 v83, v83, v148
	v_cvt_pk_bf16_f32 v91, v82, v83
	ds_write2st64_b64 v10, v[84:85], v[86:87] offset1:1
	ds_write2st64_b64 v10, v[88:89], v[90:91] offset0:2 offset1:3
	v_add_u32_e32 v10, 0x808, v10
	v_lshlrev_b32_e32 v82, 16, v92
	v_and_b32_e32 v83, 0xffff0000, v92
	v_mul_f32_e32 v82, v82, v149
	v_mul_f32_e32 v83, v83, v149
	v_cvt_pk_bf16_f32 v92, v82, v83
	v_lshlrev_b32_e32 v82, 16, v93
	v_and_b32_e32 v83, 0xffff0000, v93
	v_mul_f32_e32 v82, v82, v149
	v_mul_f32_e32 v83, v83, v149
	v_cvt_pk_bf16_f32 v93, v82, v83
	v_lshlrev_b32_e32 v82, 16, v94
	v_and_b32_e32 v83, 0xffff0000, v94
	v_mul_f32_e32 v82, v82, v149
	v_mul_f32_e32 v83, v83, v149
	v_cvt_pk_bf16_f32 v94, v82, v83
	v_lshlrev_b32_e32 v82, 16, v95
	v_and_b32_e32 v83, 0xffff0000, v95
	v_mul_f32_e32 v82, v82, v149
	v_mul_f32_e32 v83, v83, v149
	v_cvt_pk_bf16_f32 v95, v82, v83
	v_lshlrev_b32_e32 v82, 16, v96
	v_and_b32_e32 v83, 0xffff0000, v96
	v_mul_f32_e32 v82, v82, v149
	v_mul_f32_e32 v83, v83, v149
	v_cvt_pk_bf16_f32 v96, v82, v83
	v_lshlrev_b32_e32 v82, 16, v97
	v_and_b32_e32 v83, 0xffff0000, v97
	v_mul_f32_e32 v82, v82, v149
	v_mul_f32_e32 v83, v83, v149
	v_cvt_pk_bf16_f32 v97, v82, v83
	v_lshlrev_b32_e32 v82, 16, v98
	v_and_b32_e32 v83, 0xffff0000, v98
	v_mul_f32_e32 v82, v82, v149
	v_mul_f32_e32 v83, v83, v149
	v_cvt_pk_bf16_f32 v98, v82, v83
	v_lshlrev_b32_e32 v82, 16, v99
	v_and_b32_e32 v83, 0xffff0000, v99
	v_mul_f32_e32 v82, v82, v149
	v_mul_f32_e32 v83, v83, v149
	v_cvt_pk_bf16_f32 v99, v82, v83
	ds_write2st64_b64 v10, v[92:93], v[94:95] offset1:1
	ds_write2st64_b64 v10, v[96:97], v[98:99] offset0:2 offset1:3
	v_add_u32_e32 v10, 0x808, v10
	v_lshlrev_b32_e32 v82, 16, v100
	v_and_b32_e32 v83, 0xffff0000, v100
	v_mul_f32_e32 v82, v82, v150
	v_mul_f32_e32 v83, v83, v150
	v_cvt_pk_bf16_f32 v100, v82, v83
	v_lshlrev_b32_e32 v82, 16, v101
	v_and_b32_e32 v83, 0xffff0000, v101
	v_mul_f32_e32 v82, v82, v150
	v_mul_f32_e32 v83, v83, v150
	v_cvt_pk_bf16_f32 v101, v82, v83
	v_lshlrev_b32_e32 v82, 16, v102
	v_and_b32_e32 v83, 0xffff0000, v102
	v_mul_f32_e32 v82, v82, v150
	v_mul_f32_e32 v83, v83, v150
	v_cvt_pk_bf16_f32 v102, v82, v83
	v_lshlrev_b32_e32 v82, 16, v103
	v_and_b32_e32 v83, 0xffff0000, v103
	v_mul_f32_e32 v82, v82, v150
	v_mul_f32_e32 v83, v83, v150
	v_cvt_pk_bf16_f32 v103, v82, v83
	v_lshlrev_b32_e32 v82, 16, v104
	v_and_b32_e32 v83, 0xffff0000, v104
	v_mul_f32_e32 v82, v82, v150
	v_mul_f32_e32 v83, v83, v150
	v_cvt_pk_bf16_f32 v104, v82, v83
	v_lshlrev_b32_e32 v82, 16, v105
	v_and_b32_e32 v83, 0xffff0000, v105
	v_mul_f32_e32 v82, v82, v150
	v_mul_f32_e32 v83, v83, v150
	v_cvt_pk_bf16_f32 v105, v82, v83
	v_lshlrev_b32_e32 v82, 16, v106
	v_and_b32_e32 v83, 0xffff0000, v106
	v_mul_f32_e32 v82, v82, v150
	v_mul_f32_e32 v83, v83, v150
	v_cvt_pk_bf16_f32 v106, v82, v83
	v_lshlrev_b32_e32 v82, 16, v107
	v_and_b32_e32 v83, 0xffff0000, v107
	v_mul_f32_e32 v82, v82, v150
	v_mul_f32_e32 v83, v83, v150
	v_cvt_pk_bf16_f32 v107, v82, v83
	ds_write2st64_b64 v10, v[100:101], v[102:103] offset1:1
	ds_write2st64_b64 v10, v[104:105], v[106:107] offset0:2 offset1:3
	v_add_u32_e32 v10, 0x808, v10
	v_lshlrev_b32_e32 v82, 16, v108
	v_and_b32_e32 v83, 0xffff0000, v108
	v_mul_f32_e32 v82, v82, v151
	v_mul_f32_e32 v83, v83, v151
	v_cvt_pk_bf16_f32 v108, v82, v83
	v_lshlrev_b32_e32 v82, 16, v109
	v_and_b32_e32 v83, 0xffff0000, v109
	v_mul_f32_e32 v82, v82, v151
	v_mul_f32_e32 v83, v83, v151
	v_cvt_pk_bf16_f32 v109, v82, v83
	v_lshlrev_b32_e32 v82, 16, v110
	v_and_b32_e32 v83, 0xffff0000, v110
	v_mul_f32_e32 v82, v82, v151
	v_mul_f32_e32 v83, v83, v151
	v_cvt_pk_bf16_f32 v110, v82, v83
	v_lshlrev_b32_e32 v82, 16, v111
	v_and_b32_e32 v83, 0xffff0000, v111
	v_mul_f32_e32 v82, v82, v151
	v_mul_f32_e32 v83, v83, v151
	v_cvt_pk_bf16_f32 v111, v82, v83
	v_lshlrev_b32_e32 v82, 16, v112
	v_and_b32_e32 v83, 0xffff0000, v112
	v_mul_f32_e32 v82, v82, v151
	v_mul_f32_e32 v83, v83, v151
	v_cvt_pk_bf16_f32 v112, v82, v83
	v_lshlrev_b32_e32 v82, 16, v113
	v_and_b32_e32 v83, 0xffff0000, v113
	v_mul_f32_e32 v82, v82, v151
	v_mul_f32_e32 v83, v83, v151
	v_cvt_pk_bf16_f32 v113, v82, v83
	v_lshlrev_b32_e32 v82, 16, v114
	v_and_b32_e32 v83, 0xffff0000, v114
	v_mul_f32_e32 v82, v82, v151
	v_mul_f32_e32 v83, v83, v151
	v_cvt_pk_bf16_f32 v114, v82, v83
	v_lshlrev_b32_e32 v82, 16, v115
	v_and_b32_e32 v83, 0xffff0000, v115
	v_mul_f32_e32 v82, v82, v151
	v_mul_f32_e32 v83, v83, v151
	v_cvt_pk_bf16_f32 v115, v82, v83
	ds_write2st64_b64 v10, v[108:109], v[110:111] offset1:1
	ds_write2st64_b64 v10, v[112:113], v[114:115] offset0:2 offset1:3
	v_add_u32_e32 v10, 0x808, v10
	v_lshlrev_b32_e32 v82, 16, v116
	v_and_b32_e32 v83, 0xffff0000, v116
	v_mul_f32_e32 v82, v82, v152
	v_mul_f32_e32 v83, v83, v152
	v_cvt_pk_bf16_f32 v116, v82, v83
	v_lshlrev_b32_e32 v82, 16, v117
	v_and_b32_e32 v83, 0xffff0000, v117
	v_mul_f32_e32 v82, v82, v152
	v_mul_f32_e32 v83, v83, v152
	v_cvt_pk_bf16_f32 v117, v82, v83
	v_lshlrev_b32_e32 v82, 16, v118
	v_and_b32_e32 v83, 0xffff0000, v118
	v_mul_f32_e32 v82, v82, v152
	v_mul_f32_e32 v83, v83, v152
	v_cvt_pk_bf16_f32 v118, v82, v83
	v_lshlrev_b32_e32 v82, 16, v119
	v_and_b32_e32 v83, 0xffff0000, v119
	v_mul_f32_e32 v82, v82, v152
	v_mul_f32_e32 v83, v83, v152
	v_cvt_pk_bf16_f32 v119, v82, v83
	v_lshlrev_b32_e32 v82, 16, v120
	v_and_b32_e32 v83, 0xffff0000, v120
	v_mul_f32_e32 v82, v82, v152
	v_mul_f32_e32 v83, v83, v152
	v_cvt_pk_bf16_f32 v120, v82, v83
	v_lshlrev_b32_e32 v82, 16, v121
	v_and_b32_e32 v83, 0xffff0000, v121
	v_mul_f32_e32 v82, v82, v152
	v_mul_f32_e32 v83, v83, v152
	v_cvt_pk_bf16_f32 v121, v82, v83
	v_lshlrev_b32_e32 v82, 16, v122
	v_and_b32_e32 v83, 0xffff0000, v122
	v_mul_f32_e32 v82, v82, v152
	v_mul_f32_e32 v83, v83, v152
	v_cvt_pk_bf16_f32 v122, v82, v83
	v_lshlrev_b32_e32 v82, 16, v123
	v_and_b32_e32 v83, 0xffff0000, v123
	v_mul_f32_e32 v82, v82, v152
	v_mul_f32_e32 v83, v83, v152
	v_cvt_pk_bf16_f32 v123, v82, v83
	ds_write2st64_b64 v10, v[116:117], v[118:119] offset1:1
	ds_write2st64_b64 v10, v[120:121], v[122:123] offset0:2 offset1:3
	v_add_u32_e32 v10, 0x808, v10
	v_lshlrev_b32_e32 v82, 16, v124
	v_and_b32_e32 v83, 0xffff0000, v124
	v_mul_f32_e32 v82, v82, v153
	v_mul_f32_e32 v83, v83, v153
	v_cvt_pk_bf16_f32 v124, v82, v83
	v_lshlrev_b32_e32 v82, 16, v125
	v_and_b32_e32 v83, 0xffff0000, v125
	v_mul_f32_e32 v82, v82, v153
	v_mul_f32_e32 v83, v83, v153
	v_cvt_pk_bf16_f32 v125, v82, v83
	v_lshlrev_b32_e32 v82, 16, v126
	v_and_b32_e32 v83, 0xffff0000, v126
	v_mul_f32_e32 v82, v82, v153
	v_mul_f32_e32 v83, v83, v153
	v_cvt_pk_bf16_f32 v126, v82, v83
	v_lshlrev_b32_e32 v82, 16, v127
	v_and_b32_e32 v83, 0xffff0000, v127
	v_mul_f32_e32 v82, v82, v153
	v_mul_f32_e32 v83, v83, v153
	v_cvt_pk_bf16_f32 v127, v82, v83
	v_lshlrev_b32_e32 v82, 16, v128
	v_and_b32_e32 v83, 0xffff0000, v128
	v_mul_f32_e32 v82, v82, v153
	v_mul_f32_e32 v83, v83, v153
	v_cvt_pk_bf16_f32 v128, v82, v83
	v_lshlrev_b32_e32 v82, 16, v129
	v_and_b32_e32 v83, 0xffff0000, v129
	v_mul_f32_e32 v82, v82, v153
	v_mul_f32_e32 v83, v83, v153
	v_cvt_pk_bf16_f32 v129, v82, v83
	v_lshlrev_b32_e32 v82, 16, v130
	v_and_b32_e32 v83, 0xffff0000, v130
	v_mul_f32_e32 v82, v82, v153
	v_mul_f32_e32 v83, v83, v153
	v_cvt_pk_bf16_f32 v130, v82, v83
	v_lshlrev_b32_e32 v82, 16, v131
	v_and_b32_e32 v83, 0xffff0000, v131
	v_mul_f32_e32 v82, v82, v153
	v_mul_f32_e32 v83, v83, v153
	v_cvt_pk_bf16_f32 v131, v82, v83
	ds_write2st64_b64 v10, v[124:125], v[126:127] offset1:1
	ds_write2st64_b64 v10, v[128:129], v[130:131] offset0:2 offset1:3
	v_add_u32_e32 v10, 0x808, v10
	v_lshlrev_b32_e32 v82, 16, v132
	v_and_b32_e32 v83, 0xffff0000, v132
	v_mul_f32_e32 v82, v82, v154
	v_mul_f32_e32 v83, v83, v154
	v_cvt_pk_bf16_f32 v132, v82, v83
	v_lshlrev_b32_e32 v82, 16, v133
	v_and_b32_e32 v83, 0xffff0000, v133
	v_mul_f32_e32 v82, v82, v154
	v_mul_f32_e32 v83, v83, v154
	v_cvt_pk_bf16_f32 v133, v82, v83
	v_lshlrev_b32_e32 v82, 16, v134
	v_and_b32_e32 v83, 0xffff0000, v134
	v_mul_f32_e32 v82, v82, v154
	v_mul_f32_e32 v83, v83, v154
	v_cvt_pk_bf16_f32 v134, v82, v83
	v_lshlrev_b32_e32 v82, 16, v135
	v_and_b32_e32 v83, 0xffff0000, v135
	v_mul_f32_e32 v82, v82, v154
	v_mul_f32_e32 v83, v83, v154
	v_cvt_pk_bf16_f32 v135, v82, v83
	v_lshlrev_b32_e32 v82, 16, v136
	v_and_b32_e32 v83, 0xffff0000, v136
	v_mul_f32_e32 v82, v82, v154
	v_mul_f32_e32 v83, v83, v154
	v_cvt_pk_bf16_f32 v136, v82, v83
	v_lshlrev_b32_e32 v82, 16, v137
	v_and_b32_e32 v83, 0xffff0000, v137
	v_mul_f32_e32 v82, v82, v154
	v_mul_f32_e32 v83, v83, v154
	v_cvt_pk_bf16_f32 v137, v82, v83
	v_lshlrev_b32_e32 v82, 16, v138
	v_and_b32_e32 v83, 0xffff0000, v138
	v_mul_f32_e32 v82, v82, v154
	v_mul_f32_e32 v83, v83, v154
	v_cvt_pk_bf16_f32 v138, v82, v83
	v_lshlrev_b32_e32 v82, 16, v139
	v_and_b32_e32 v83, 0xffff0000, v139
	v_mul_f32_e32 v82, v82, v154
	v_mul_f32_e32 v83, v83, v154
	v_cvt_pk_bf16_f32 v139, v82, v83
	ds_write2st64_b64 v10, v[132:133], v[134:135] offset1:1
	ds_write2st64_b64 v10, v[136:137], v[138:139] offset0:2 offset1:3
	v_add_u32_e32 v10, 0x808, v10
	v_lshlrev_b32_e32 v82, 16, v140
	v_and_b32_e32 v83, 0xffff0000, v140
	v_mul_f32_e32 v82, v82, v155
	v_mul_f32_e32 v83, v83, v155
	v_cvt_pk_bf16_f32 v140, v82, v83
	v_lshlrev_b32_e32 v82, 16, v141
	v_and_b32_e32 v83, 0xffff0000, v141
	v_mul_f32_e32 v82, v82, v155
	v_mul_f32_e32 v83, v83, v155
	v_cvt_pk_bf16_f32 v141, v82, v83
	v_lshlrev_b32_e32 v82, 16, v142
	v_and_b32_e32 v83, 0xffff0000, v142
	v_mul_f32_e32 v82, v82, v155
	v_mul_f32_e32 v83, v83, v155
	v_cvt_pk_bf16_f32 v142, v82, v83
	v_lshlrev_b32_e32 v82, 16, v143
	v_and_b32_e32 v83, 0xffff0000, v143
	v_mul_f32_e32 v82, v82, v155
	v_mul_f32_e32 v83, v83, v155
	v_cvt_pk_bf16_f32 v143, v82, v83
	v_lshlrev_b32_e32 v82, 16, v144
	v_and_b32_e32 v83, 0xffff0000, v144
	v_mul_f32_e32 v82, v82, v155
	v_mul_f32_e32 v83, v83, v155
	v_cvt_pk_bf16_f32 v144, v82, v83
	v_lshlrev_b32_e32 v82, 16, v145
	v_and_b32_e32 v83, 0xffff0000, v145
	v_mul_f32_e32 v82, v82, v155
	v_mul_f32_e32 v83, v83, v155
	v_cvt_pk_bf16_f32 v145, v82, v83
	v_lshlrev_b32_e32 v82, 16, v146
	v_and_b32_e32 v83, 0xffff0000, v146
	v_mul_f32_e32 v82, v82, v155
	v_mul_f32_e32 v83, v83, v155
	v_cvt_pk_bf16_f32 v146, v82, v83
	v_lshlrev_b32_e32 v82, 16, v147
	v_and_b32_e32 v83, 0xffff0000, v147
	v_mul_f32_e32 v82, v82, v155
	v_mul_f32_e32 v83, v83, v155
	v_cvt_pk_bf16_f32 v147, v82, v83
	ds_write2st64_b64 v10, v[140:141], v[142:143] offset1:1
	ds_write2st64_b64 v10, v[144:145], v[146:147] offset0:2 offset1:3
	v_add_u32_e32 v10, 0x808, v10
	s_waitcnt lgkmcnt(0)
	s_barrier
	v_mbcnt_lo_u32_b32 v91, -1, 0
	v_mbcnt_hi_u32_b32 v91, -1, v91
	v_readlane_b32 s9, v254, 63
	v_and_b32_e32 v88, 7, v91
	v_lshrrev_b32_e32 v89, 3, v91
	v_lshl_add_u32 v89, s9, 3, v89
	v_mul_u32_u24_e32 v90, 16448, v88
	v_lshl_add_u32 v90, v89, 2, v90
	v_mul_u32_u24_e32 v89, 0xc000, v89
	v_lshl_add_u32 v89, v88, 4, v89
	v_add_u32_e32 v88, 0x6000, v89
	s_lshl_b32 s8, s0, 7
	v_readlane_b32 s10, v255, 7
	v_readlane_b32 s11, v255, 8
	s_add_u32 s10, s10, 0x10000000
	s_addc_u32 s11, s11, 0
	s_add_u32 s10, s10, s8
	s_addc_u32 s11, s11, 0
	s_mov_b32 s1, 0x5040100
	s_mov_b32 s3, 0x7060302
	ds_read_b32 v70, v90 offset:0
	ds_read_b32 v71, v90 offset:2056
	ds_read_b32 v72, v90 offset:4112
	ds_read_b32 v73, v90 offset:6168
	ds_read_b32 v74, v90 offset:8224
	ds_read_b32 v75, v90 offset:10280
	ds_read_b32 v76, v90 offset:12336
	ds_read_b32 v77, v90 offset:14392
	ds_read_b32 v92, v90 offset:256
	ds_read_b32 v93, v90 offset:2312
	ds_read_b32 v94, v90 offset:4368
	ds_read_b32 v95, v90 offset:6424
	ds_read_b32 v96, v90 offset:8480
	ds_read_b32 v97, v90 offset:10536
	ds_read_b32 v98, v90 offset:12592
	ds_read_b32 v99, v90 offset:14648
	s_waitcnt lgkmcnt(8)
	v_perm_b32 v80, v71, v70, s1
	v_perm_b32 v81, v73, v72, s1
	v_perm_b32 v82, v75, v74, s1
	v_perm_b32 v83, v77, v76, s1
	v_perm_b32 v84, v71, v70, s3
	v_perm_b32 v85, v73, v72, s3
	v_perm_b32 v86, v75, v74, s3
	v_perm_b32 v87, v77, v76, s3
	global_store_dwordx4 v89, v[80:83], s[10:11] sc1
	global_store_dwordx4 v88, v[84:87], s[10:11] sc1
	s_add_u32 s10, s10, 0x300000
	s_addc_u32 s11, s11, 0
	ds_read_b32 v70, v90 offset:512
	ds_read_b32 v71, v90 offset:2568
	ds_read_b32 v72, v90 offset:4624
	ds_read_b32 v73, v90 offset:6680
	ds_read_b32 v74, v90 offset:8736
	ds_read_b32 v75, v90 offset:10792
	ds_read_b32 v76, v90 offset:12848
	ds_read_b32 v77, v90 offset:14904
	s_waitcnt lgkmcnt(8)
	v_perm_b32 v80, v93, v92, s1
	v_perm_b32 v81, v95, v94, s1
	v_perm_b32 v82, v97, v96, s1
	v_perm_b32 v83, v99, v98, s1
	v_perm_b32 v84, v93, v92, s3
	v_perm_b32 v85, v95, v94, s3
	v_perm_b32 v86, v97, v96, s3
	v_perm_b32 v87, v99, v98, s3
	global_store_dwordx4 v89, v[80:83], s[10:11] sc1
	global_store_dwordx4 v88, v[84:87], s[10:11] sc1
	s_add_u32 s10, s10, 0x300000
	s_addc_u32 s11, s11, 0
	ds_read_b32 v92, v90 offset:768
	ds_read_b32 v93, v90 offset:2824
	ds_read_b32 v94, v90 offset:4880
	ds_read_b32 v95, v90 offset:6936
	ds_read_b32 v96, v90 offset:8992
	ds_read_b32 v97, v90 offset:11048
	ds_read_b32 v98, v90 offset:13104
	ds_read_b32 v99, v90 offset:15160
	s_waitcnt lgkmcnt(8)
	v_perm_b32 v80, v71, v70, s1
	v_perm_b32 v81, v73, v72, s1
	v_perm_b32 v82, v75, v74, s1
	v_perm_b32 v83, v77, v76, s1
	v_perm_b32 v84, v71, v70, s3
	v_perm_b32 v85, v73, v72, s3
	v_perm_b32 v86, v75, v74, s3
	v_perm_b32 v87, v77, v76, s3
	global_store_dwordx4 v89, v[80:83], s[10:11] sc1
	global_store_dwordx4 v88, v[84:87], s[10:11] sc1
	s_add_u32 s10, s10, 0x300000
	s_addc_u32 s11, s11, 0
	ds_read_b32 v70, v90 offset:1024
	ds_read_b32 v71, v90 offset:3080
	ds_read_b32 v72, v90 offset:5136
	ds_read_b32 v73, v90 offset:7192
	ds_read_b32 v74, v90 offset:9248
	ds_read_b32 v75, v90 offset:11304
	ds_read_b32 v76, v90 offset:13360
	ds_read_b32 v77, v90 offset:15416
	s_waitcnt lgkmcnt(8)
	v_perm_b32 v80, v93, v92, s1
	v_perm_b32 v81, v95, v94, s1
	v_perm_b32 v82, v97, v96, s1
	v_perm_b32 v83, v99, v98, s1
	v_perm_b32 v84, v93, v92, s3
	v_perm_b32 v85, v95, v94, s3
	v_perm_b32 v86, v97, v96, s3
	v_perm_b32 v87, v99, v98, s3
	global_store_dwordx4 v89, v[80:83], s[10:11] sc1
	global_store_dwordx4 v88, v[84:87], s[10:11] sc1
	s_add_u32 s10, s10, 0x300000
	s_addc_u32 s11, s11, 0
	ds_read_b32 v92, v90 offset:1280
	ds_read_b32 v93, v90 offset:3336
	ds_read_b32 v94, v90 offset:5392
	ds_read_b32 v95, v90 offset:7448
	ds_read_b32 v96, v90 offset:9504
	ds_read_b32 v97, v90 offset:11560
	ds_read_b32 v98, v90 offset:13616
	ds_read_b32 v99, v90 offset:15672
	s_waitcnt lgkmcnt(8)
	v_perm_b32 v80, v71, v70, s1
	v_perm_b32 v81, v73, v72, s1
	v_perm_b32 v82, v75, v74, s1
	v_perm_b32 v83, v77, v76, s1
	v_perm_b32 v84, v71, v70, s3
	v_perm_b32 v85, v73, v72, s3
	v_perm_b32 v86, v75, v74, s3
	v_perm_b32 v87, v77, v76, s3
	global_store_dwordx4 v89, v[80:83], s[10:11] sc1
	global_store_dwordx4 v88, v[84:87], s[10:11] sc1
	s_add_u32 s10, s10, 0x300000
	s_addc_u32 s11, s11, 0
	ds_read_b32 v70, v90 offset:1536
	ds_read_b32 v71, v90 offset:3592
	ds_read_b32 v72, v90 offset:5648
	ds_read_b32 v73, v90 offset:7704
	ds_read_b32 v74, v90 offset:9760
	ds_read_b32 v75, v90 offset:11816
	ds_read_b32 v76, v90 offset:13872
	ds_read_b32 v77, v90 offset:15928
	s_waitcnt lgkmcnt(8)
	v_perm_b32 v80, v93, v92, s1
	v_perm_b32 v81, v95, v94, s1
	v_perm_b32 v82, v97, v96, s1
	v_perm_b32 v83, v99, v98, s1
	v_perm_b32 v84, v93, v92, s3
	v_perm_b32 v85, v95, v94, s3
	v_perm_b32 v86, v97, v96, s3
	v_perm_b32 v87, v99, v98, s3
	global_store_dwordx4 v89, v[80:83], s[10:11] sc1
	global_store_dwordx4 v88, v[84:87], s[10:11] sc1
	s_add_u32 s10, s10, 0x300000
	s_addc_u32 s11, s11, 0
	ds_read_b32 v92, v90 offset:1792
	ds_read_b32 v93, v90 offset:3848
	ds_read_b32 v94, v90 offset:5904
	ds_read_b32 v95, v90 offset:7960
	ds_read_b32 v96, v90 offset:10016
	ds_read_b32 v97, v90 offset:12072
	ds_read_b32 v98, v90 offset:14128
	ds_read_b32 v99, v90 offset:16184
	s_waitcnt lgkmcnt(8)
	v_perm_b32 v80, v71, v70, s1
	v_perm_b32 v81, v73, v72, s1
	v_perm_b32 v82, v75, v74, s1
	v_perm_b32 v83, v77, v76, s1
	v_perm_b32 v84, v71, v70, s3
	v_perm_b32 v85, v73, v72, s3
	v_perm_b32 v86, v75, v74, s3
	v_perm_b32 v87, v77, v76, s3
	global_store_dwordx4 v89, v[80:83], s[10:11] sc1
	global_store_dwordx4 v88, v[84:87], s[10:11] sc1
	s_add_u32 s10, s10, 0x300000
	s_addc_u32 s11, s11, 0
	s_waitcnt lgkmcnt(0)
	v_perm_b32 v80, v93, v92, s1
	v_perm_b32 v81, v95, v94, s1
	v_perm_b32 v82, v97, v96, s1
	v_perm_b32 v83, v99, v98, s1
	v_perm_b32 v84, v93, v92, s3
	v_perm_b32 v85, v95, v94, s3
	v_perm_b32 v86, v97, v96, s3
	v_perm_b32 v87, v99, v98, s3
	global_store_dwordx4 v89, v[80:83], s[10:11] sc1
	global_store_dwordx4 v88, v[84:87], s[10:11] sc1
	s_add_i32 s0, s0, s78
	s_add_i32 s6, s6, s35
	s_cmpk_gt_i32 s0, 0xbf
	s_barrier
	s_cbranch_scc0 .LBB0_119

.Lnt_bar:
	s_barrier
	v_readlane_b32 s10, v255, 5
	v_readlane_b32 s11, v255, 6
	s_lshl_b64 s[12:13], s[16:17], 12
	s_add_u32 s10, s10, s12
	s_addc_u32 s11, s11, s13
	s_mov_b32 s3, 0x3a800000
	global_load_dwordx4 v[70:73], v201, s[10:11] offset:0
	global_load_dwordx4 v[74:77], v201, s[10:11] offset:16
	global_load_dwordx4 v[78:81], v201, s[10:11] offset:2048
	global_load_dwordx4 v[82:85], v201, s[10:11] offset:2064
	s_add_u32 s10, s10, 0x1000
	s_addc_u32 s11, s11, 0
	global_load_dwordx4 v[86:89], v201, s[10:11] offset:0
	global_load_dwordx4 v[90:93], v201, s[10:11] offset:16
	global_load_dwordx4 v[94:97], v201, s[10:11] offset:2048
	global_load_dwordx4 v[98:101], v201, s[10:11] offset:2064
	s_add_u32 s10, s10, 0x1000
	s_addc_u32 s11, s11, 0
	global_load_dwordx4 v[102:105], v201, s[10:11] offset:0
	global_load_dwordx4 v[106:109], v201, s[10:11] offset:16
	global_load_dwordx4 v[110:113], v201, s[10:11] offset:2048
	global_load_dwordx4 v[114:117], v201, s[10:11] offset:2064
	s_add_u32 s10, s10, 0x1000
	s_addc_u32 s11, s11, 0
	global_load_dwordx4 v[118:121], v201, s[10:11] offset:0
	global_load_dwordx4 v[122:125], v201, s[10:11] offset:16
	global_load_dwordx4 v[126:129], v201, s[10:11] offset:2048
	global_load_dwordx4 v[130:133], v201, s[10:11] offset:2064
	s_add_u32 s10, s10, 0x1000
	s_addc_u32 s11, s11, 0
	s_waitcnt vmcnt(16)
	v_add_f32_e32 v150, 1.0, v150
	v_add_f32_e32 v151, 1.0, v151
	v_add_f32_e32 v152, 1.0, v152
	v_add_f32_e32 v153, 1.0, v153
	v_add_f32_e32 v154, 1.0, v154
	v_add_f32_e32 v155, 1.0, v155
	v_add_f32_e32 v156, 1.0, v156
	v_add_f32_e32 v157, 1.0, v157
	v_add_f32_e32 v158, 1.0, v158
	v_add_f32_e32 v159, 1.0, v159
	v_add_f32_e32 v160, 1.0, v160
	v_add_f32_e32 v161, 1.0, v161
	v_add_f32_e32 v162, 1.0, v162
	v_add_f32_e32 v163, 1.0, v163
	v_add_f32_e32 v164, 1.0, v164
	v_add_f32_e32 v165, 1.0, v165
	v_mul_f32_e32 v150, v134, v150
	v_mul_f32_e32 v151, v135, v151
	v_mul_f32_e32 v152, v136, v152
	v_mul_f32_e32 v153, v137, v153
	v_mul_f32_e32 v154, v138, v154
	v_mul_f32_e32 v155, v139, v155
	v_mul_f32_e32 v156, v140, v156
	v_mul_f32_e32 v157, v141, v157
	v_mul_f32_e32 v158, v142, v158
	v_mul_f32_e32 v159, v143, v159
	v_mul_f32_e32 v160, v144, v160
	v_mul_f32_e32 v161, v145, v161
	v_mul_f32_e32 v162, v146, v162
	v_mul_f32_e32 v163, v147, v163
	v_mul_f32_e32 v164, v148, v164
	v_mul_f32_e32 v165, v149, v165
	s_waitcnt vmcnt(12)
	v_mul_f32_e32 v186, v70, v70
	v_fmac_f32_e32 v186, v71, v71
	v_fmac_f32_e32 v186, v72, v72
	v_fmac_f32_e32 v186, v73, v73
	v_fmac_f32_e32 v186, v74, v74
	v_fmac_f32_e32 v186, v75, v75
	v_fmac_f32_e32 v186, v76, v76
	v_fmac_f32_e32 v186, v77, v77
	v_fmac_f32_e32 v186, v78, v78
	v_fmac_f32_e32 v186, v79, v79
	v_fmac_f32_e32 v186, v80, v80
	v_fmac_f32_e32 v186, v81, v81
	v_fmac_f32_e32 v186, v82, v82
	v_fmac_f32_e32 v186, v83, v83
	v_fmac_f32_e32 v186, v84, v84
	v_fmac_f32_e32 v186, v85, v85
	s_waitcnt vmcnt(8)
	v_mul_f32_e32 v187, v86, v86
	v_fmac_f32_e32 v187, v87, v87
	v_fmac_f32_e32 v187, v88, v88
	v_fmac_f32_e32 v187, v89, v89
	v_fmac_f32_e32 v187, v90, v90
	v_fmac_f32_e32 v187, v91, v91
	v_fmac_f32_e32 v187, v92, v92
	v_fmac_f32_e32 v187, v93, v93
	v_fmac_f32_e32 v187, v94, v94
	v_fmac_f32_e32 v187, v95, v95
	v_fmac_f32_e32 v187, v96, v96
	v_fmac_f32_e32 v187, v97, v97
	v_fmac_f32_e32 v187, v98, v98
	v_fmac_f32_e32 v187, v99, v99
	v_fmac_f32_e32 v187, v100, v100
	v_fmac_f32_e32 v187, v101, v101
	s_waitcnt vmcnt(4)
	v_mul_f32_e32 v188, v102, v102
	v_fmac_f32_e32 v188, v103, v103
	v_fmac_f32_e32 v188, v104, v104
	v_fmac_f32_e32 v188, v105, v105
	v_fmac_f32_e32 v188, v106, v106
	v_fmac_f32_e32 v188, v107, v107
	v_fmac_f32_e32 v188, v108, v108
	v_fmac_f32_e32 v188, v109, v109
	v_fmac_f32_e32 v188, v110, v110
	v_fmac_f32_e32 v188, v111, v111
	v_fmac_f32_e32 v188, v112, v112
	v_fmac_f32_e32 v188, v113, v113
	v_fmac_f32_e32 v188, v114, v114
	v_fmac_f32_e32 v188, v115, v115
	v_fmac_f32_e32 v188, v116, v116
	v_fmac_f32_e32 v188, v117, v117
	s_waitcnt vmcnt(0)
	v_mul_f32_e32 v189, v118, v118
	v_fmac_f32_e32 v189, v119, v119
	v_fmac_f32_e32 v189, v120, v120
	v_fmac_f32_e32 v189, v121, v121
	v_fmac_f32_e32 v189, v122, v122
	v_fmac_f32_e32 v189, v123, v123
	v_fmac_f32_e32 v189, v124, v124
	v_fmac_f32_e32 v189, v125, v125
	v_fmac_f32_e32 v189, v126, v126
	v_fmac_f32_e32 v189, v127, v127
	v_fmac_f32_e32 v189, v128, v128
	v_fmac_f32_e32 v189, v129, v129
	v_fmac_f32_e32 v189, v130, v130
	v_fmac_f32_e32 v189, v131, v131
	v_fmac_f32_e32 v189, v132, v132
	v_fmac_f32_e32 v189, v133, v133
	s_nop 1
	v_add_f32_dpp v186, v186, v186 row_ror:8 row_mask:0xf bank_mask:0xf
	v_add_f32_dpp v187, v187, v187 row_ror:8 row_mask:0xf bank_mask:0xf
	v_add_f32_dpp v188, v188, v188 row_ror:8 row_mask:0xf bank_mask:0xf
	v_add_f32_dpp v189, v189, v189 row_ror:8 row_mask:0xf bank_mask:0xf
	v_add_f32_dpp v186, v186, v186 row_ror:4 row_mask:0xf bank_mask:0xf
	v_add_f32_dpp v187, v187, v187 row_ror:4 row_mask:0xf bank_mask:0xf
	v_add_f32_dpp v188, v188, v188 row_ror:4 row_mask:0xf bank_mask:0xf
	v_add_f32_dpp v189, v189, v189 row_ror:4 row_mask:0xf bank_mask:0xf
	v_add_f32_dpp v186, v186, v186 row_ror:2 row_mask:0xf bank_mask:0xf
	v_add_f32_dpp v187, v187, v187 row_ror:2 row_mask:0xf bank_mask:0xf
	v_add_f32_dpp v188, v188, v188 row_ror:2 row_mask:0xf bank_mask:0xf
	v_add_f32_dpp v189, v189, v189 row_ror:2 row_mask:0xf bank_mask:0xf
	v_add_f32_dpp v186, v186, v186 row_ror:1 row_mask:0xf bank_mask:0xf
	v_add_f32_dpp v187, v187, v187 row_ror:1 row_mask:0xf bank_mask:0xf
	v_add_f32_dpp v188, v188, v188 row_ror:1 row_mask:0xf bank_mask:0xf
	v_add_f32_dpp v189, v189, v189 row_ror:1 row_mask:0xf bank_mask:0xf
	v_mov_b32_e32 v190, v186
	v_mov_b32_e32 v191, v187
	v_mov_b32_e32 v192, v188
	v_mov_b32_e32 v193, v189
	s_nop 1
	v_permlane16_swap_b32_e32 v190, v186
	v_permlane16_swap_b32_e32 v191, v187
	v_permlane16_swap_b32_e32 v192, v188
	v_permlane16_swap_b32_e32 v193, v189
	v_add_f32_e32 v186, v186, v190
	v_add_f32_e32 v187, v187, v191
	v_add_f32_e32 v188, v188, v192
	v_add_f32_e32 v189, v189, v193
	v_mov_b32_e32 v190, v186
	v_mov_b32_e32 v191, v187
	v_mov_b32_e32 v192, v188
	v_mov_b32_e32 v193, v189
	s_nop 1
	v_permlane32_swap_b32_e32 v190, v186
	v_permlane32_swap_b32_e32 v191, v187
	v_permlane32_swap_b32_e32 v192, v188
	v_permlane32_swap_b32_e32 v193, v189
	v_add_f32_e32 v186, v186, v190
	v_add_f32_e32 v187, v187, v191
	v_add_f32_e32 v188, v188, v192
	v_add_f32_e32 v189, v189, v193
	v_fma_f32 v186, v186, s3, v167
	v_fma_f32 v187, v187, s3, v167
	v_fma_f32 v188, v188, s3, v167
	v_fma_f32 v189, v189, s3, v167
	v_rsq_f32_e32 v186, v186
	v_rsq_f32_e32 v187, v187
	v_rsq_f32_e32 v188, v188
	v_rsq_f32_e32 v189, v189
	s_nop 0
	v_mul_f32_e32 v70, v70, v186
	v_mul_f32_e32 v71, v71, v186
	v_mul_f32_e32 v72, v72, v186
	v_mul_f32_e32 v73, v73, v186
	v_mul_f32_e32 v74, v74, v186
	v_mul_f32_e32 v75, v75, v186
	v_mul_f32_e32 v76, v76, v186
	v_mul_f32_e32 v77, v77, v186
	v_mul_f32_e32 v78, v78, v186
	v_mul_f32_e32 v79, v79, v186
	v_mul_f32_e32 v80, v80, v186
	v_mul_f32_e32 v81, v81, v186
	v_mul_f32_e32 v82, v82, v186
	v_mul_f32_e32 v83, v83, v186
	v_mul_f32_e32 v84, v84, v186
	v_mul_f32_e32 v85, v85, v186
	v_fma_f32 v70, v70, v150, v170
	v_fma_f32 v71, v71, v151, v171
	v_fma_f32 v72, v72, v152, v172
	v_fma_f32 v73, v73, v153, v173
	v_fma_f32 v74, v74, v154, v174
	v_fma_f32 v75, v75, v155, v175
	v_fma_f32 v76, v76, v156, v176
	v_fma_f32 v77, v77, v157, v177
	v_fma_f32 v78, v78, v158, v178
	v_fma_f32 v79, v79, v159, v179
	v_fma_f32 v80, v80, v160, v180
	v_fma_f32 v81, v81, v161, v181
	v_fma_f32 v82, v82, v162, v182
	v_fma_f32 v83, v83, v163, v183
	v_fma_f32 v84, v84, v164, v184
	v_fma_f32 v85, v85, v165, v185
	v_cvt_pk_bf16_f32 v70, v70, v71
	v_cvt_pk_bf16_f32 v71, v72, v73
	v_cvt_pk_bf16_f32 v72, v74, v75
	v_cvt_pk_bf16_f32 v73, v76, v77
	v_cvt_pk_bf16_f32 v78, v78, v79
	v_cvt_pk_bf16_f32 v79, v80, v81
	v_cvt_pk_bf16_f32 v80, v82, v83
	v_cvt_pk_bf16_f32 v81, v84, v85
	ds_write_b64 v202, v[70:71] offset:0
	ds_write_b64 v202, v[72:73] offset:8
	ds_write_b64 v202, v[78:79] offset:1024
	ds_write_b64 v202, v[80:81] offset:1032
	v_mul_f32_e32 v86, v86, v187
	v_mul_f32_e32 v87, v87, v187
	v_mul_f32_e32 v88, v88, v187
	v_mul_f32_e32 v89, v89, v187
	v_mul_f32_e32 v90, v90, v187
	v_mul_f32_e32 v91, v91, v187
	v_mul_f32_e32 v92, v92, v187
	v_mul_f32_e32 v93, v93, v187
	v_mul_f32_e32 v94, v94, v187
	v_mul_f32_e32 v95, v95, v187
	v_mul_f32_e32 v96, v96, v187
	v_mul_f32_e32 v97, v97, v187
	v_mul_f32_e32 v98, v98, v187
	v_mul_f32_e32 v99, v99, v187
	v_mul_f32_e32 v100, v100, v187
	v_mul_f32_e32 v101, v101, v187
	v_fma_f32 v86, v86, v150, v170
	v_fma_f32 v87, v87, v151, v171
	v_fma_f32 v88, v88, v152, v172
	v_fma_f32 v89, v89, v153, v173
	v_fma_f32 v90, v90, v154, v174
	v_fma_f32 v91, v91, v155, v175
	v_fma_f32 v92, v92, v156, v176
	v_fma_f32 v93, v93, v157, v177
	v_fma_f32 v94, v94, v158, v178
	v_fma_f32 v95, v95, v159, v179
	v_fma_f32 v96, v96, v160, v180
	v_fma_f32 v97, v97, v161, v181
	v_fma_f32 v98, v98, v162, v182
	v_fma_f32 v99, v99, v163, v183
	v_fma_f32 v100, v100, v164, v184
	v_fma_f32 v101, v101, v165, v185
	v_cvt_pk_bf16_f32 v86, v86, v87
	v_cvt_pk_bf16_f32 v87, v88, v89
	v_cvt_pk_bf16_f32 v88, v90, v91
	v_cvt_pk_bf16_f32 v89, v92, v93
	v_cvt_pk_bf16_f32 v94, v94, v95
	v_cvt_pk_bf16_f32 v95, v96, v97
	v_cvt_pk_bf16_f32 v96, v98, v99
	v_cvt_pk_bf16_f32 v97, v100, v101
	ds_write_b64 v202, v[86:87] offset:2056
	ds_write_b64 v202, v[88:89] offset:2064
	ds_write_b64 v202, v[94:95] offset:3080
	ds_write_b64 v202, v[96:97] offset:3088
	v_mul_f32_e32 v102, v102, v188
	v_mul_f32_e32 v103, v103, v188
	v_mul_f32_e32 v104, v104, v188
	v_mul_f32_e32 v105, v105, v188
	v_mul_f32_e32 v106, v106, v188
	v_mul_f32_e32 v107, v107, v188
	v_mul_f32_e32 v108, v108, v188
	v_mul_f32_e32 v109, v109, v188
	v_mul_f32_e32 v110, v110, v188
	v_mul_f32_e32 v111, v111, v188
	v_mul_f32_e32 v112, v112, v188
	v_mul_f32_e32 v113, v113, v188
	v_mul_f32_e32 v114, v114, v188
	v_mul_f32_e32 v115, v115, v188
	v_mul_f32_e32 v116, v116, v188
	v_mul_f32_e32 v117, v117, v188
	v_fma_f32 v102, v102, v150, v170
	v_fma_f32 v103, v103, v151, v171
	v_fma_f32 v104, v104, v152, v172
	v_fma_f32 v105, v105, v153, v173
	v_fma_f32 v106, v106, v154, v174
	v_fma_f32 v107, v107, v155, v175
	v_fma_f32 v108, v108, v156, v176
	v_fma_f32 v109, v109, v157, v177
	v_fma_f32 v110, v110, v158, v178
	v_fma_f32 v111, v111, v159, v179
	v_fma_f32 v112, v112, v160, v180
	v_fma_f32 v113, v113, v161, v181
	v_fma_f32 v114, v114, v162, v182
	v_fma_f32 v115, v115, v163, v183
	v_fma_f32 v116, v116, v164, v184
	v_fma_f32 v117, v117, v165, v185
	v_cvt_pk_bf16_f32 v102, v102, v103
	v_cvt_pk_bf16_f32 v103, v104, v105
	v_cvt_pk_bf16_f32 v104, v106, v107
	v_cvt_pk_bf16_f32 v105, v108, v109
	v_cvt_pk_bf16_f32 v110, v110, v111
	v_cvt_pk_bf16_f32 v111, v112, v113
	v_cvt_pk_bf16_f32 v112, v114, v115
	v_cvt_pk_bf16_f32 v113, v116, v117
	ds_write_b64 v202, v[102:103] offset:4112
	ds_write_b64 v202, v[104:105] offset:4120
	ds_write_b64 v202, v[110:111] offset:5136
	ds_write_b64 v202, v[112:113] offset:5144
	v_mul_f32_e32 v118, v118, v189
	v_mul_f32_e32 v119, v119, v189
	v_mul_f32_e32 v120, v120, v189
	v_mul_f32_e32 v121, v121, v189
	v_mul_f32_e32 v122, v122, v189
	v_mul_f32_e32 v123, v123, v189
	v_mul_f32_e32 v124, v124, v189
	v_mul_f32_e32 v125, v125, v189
	v_mul_f32_e32 v126, v126, v189
	v_mul_f32_e32 v127, v127, v189
	v_mul_f32_e32 v128, v128, v189
	v_mul_f32_e32 v129, v129, v189
	v_mul_f32_e32 v130, v130, v189
	v_mul_f32_e32 v131, v131, v189
	v_mul_f32_e32 v132, v132, v189
	v_mul_f32_e32 v133, v133, v189
	v_fma_f32 v118, v118, v150, v170
	v_fma_f32 v119, v119, v151, v171
	v_fma_f32 v120, v120, v152, v172
	v_fma_f32 v121, v121, v153, v173
	v_fma_f32 v122, v122, v154, v174
	v_fma_f32 v123, v123, v155, v175
	v_fma_f32 v124, v124, v156, v176
	v_fma_f32 v125, v125, v157, v177
	v_fma_f32 v126, v126, v158, v178
	v_fma_f32 v127, v127, v159, v179
	v_fma_f32 v128, v128, v160, v180
	v_fma_f32 v129, v129, v161, v181
	v_fma_f32 v130, v130, v162, v182
	v_fma_f32 v131, v131, v163, v183
	v_fma_f32 v132, v132, v164, v184
	v_fma_f32 v133, v133, v165, v185
	v_cvt_pk_bf16_f32 v118, v118, v119
	v_cvt_pk_bf16_f32 v119, v120, v121
	v_cvt_pk_bf16_f32 v120, v122, v123
	v_cvt_pk_bf16_f32 v121, v124, v125
	v_cvt_pk_bf16_f32 v126, v126, v127
	v_cvt_pk_bf16_f32 v127, v128, v129
	v_cvt_pk_bf16_f32 v128, v130, v131
	v_cvt_pk_bf16_f32 v129, v132, v133
	ds_write_b64 v202, v[118:119] offset:6168
	ds_write_b64 v202, v[120:121] offset:6176
	ds_write_b64 v202, v[126:127] offset:7192
	ds_write_b64 v202, v[128:129] offset:7200
	global_load_dwordx4 v[70:73], v201, s[10:11] offset:0
	global_load_dwordx4 v[74:77], v201, s[10:11] offset:16
	global_load_dwordx4 v[78:81], v201, s[10:11] offset:2048
	global_load_dwordx4 v[82:85], v201, s[10:11] offset:2064
	s_add_u32 s10, s10, 0x1000
	s_addc_u32 s11, s11, 0
	global_load_dwordx4 v[86:89], v201, s[10:11] offset:0
	global_load_dwordx4 v[90:93], v201, s[10:11] offset:16
	global_load_dwordx4 v[94:97], v201, s[10:11] offset:2048
	global_load_dwordx4 v[98:101], v201, s[10:11] offset:2064
	s_add_u32 s10, s10, 0x1000
	s_addc_u32 s11, s11, 0
	global_load_dwordx4 v[102:105], v201, s[10:11] offset:0
	global_load_dwordx4 v[106:109], v201, s[10:11] offset:16
	global_load_dwordx4 v[110:113], v201, s[10:11] offset:2048
	global_load_dwordx4 v[114:117], v201, s[10:11] offset:2064
	s_add_u32 s10, s10, 0x1000
	s_addc_u32 s11, s11, 0
	global_load_dwordx4 v[118:121], v201, s[10:11] offset:0
	global_load_dwordx4 v[122:125], v201, s[10:11] offset:16
	global_load_dwordx4 v[126:129], v201, s[10:11] offset:2048
	global_load_dwordx4 v[130:133], v201, s[10:11] offset:2064
	s_add_u32 s10, s10, 0x1000
	s_addc_u32 s11, s11, 0
	s_waitcnt vmcnt(12)
	v_mul_f32_e32 v186, v70, v70
	v_fmac_f32_e32 v186, v71, v71
	v_fmac_f32_e32 v186, v72, v72
	v_fmac_f32_e32 v186, v73, v73
	v_fmac_f32_e32 v186, v74, v74
	v_fmac_f32_e32 v186, v75, v75
	v_fmac_f32_e32 v186, v76, v76
	v_fmac_f32_e32 v186, v77, v77
	v_fmac_f32_e32 v186, v78, v78
	v_fmac_f32_e32 v186, v79, v79
	v_fmac_f32_e32 v186, v80, v80
	v_fmac_f32_e32 v186, v81, v81
	v_fmac_f32_e32 v186, v82, v82
	v_fmac_f32_e32 v186, v83, v83
	v_fmac_f32_e32 v186, v84, v84
	v_fmac_f32_e32 v186, v85, v85
	s_waitcnt vmcnt(8)
	v_mul_f32_e32 v187, v86, v86
	v_fmac_f32_e32 v187, v87, v87
	v_fmac_f32_e32 v187, v88, v88
	v_fmac_f32_e32 v187, v89, v89
	v_fmac_f32_e32 v187, v90, v90
	v_fmac_f32_e32 v187, v91, v91
	v_fmac_f32_e32 v187, v92, v92
	v_fmac_f32_e32 v187, v93, v93
	v_fmac_f32_e32 v187, v94, v94
	v_fmac_f32_e32 v187, v95, v95
	v_fmac_f32_e32 v187, v96, v96
	v_fmac_f32_e32 v187, v97, v97
	v_fmac_f32_e32 v187, v98, v98
	v_fmac_f32_e32 v187, v99, v99
	v_fmac_f32_e32 v187, v100, v100
	v_fmac_f32_e32 v187, v101, v101
	s_waitcnt vmcnt(4)
	v_mul_f32_e32 v188, v102, v102
	v_fmac_f32_e32 v188, v103, v103
	v_fmac_f32_e32 v188, v104, v104
	v_fmac_f32_e32 v188, v105, v105
	v_fmac_f32_e32 v188, v106, v106
	v_fmac_f32_e32 v188, v107, v107
	v_fmac_f32_e32 v188, v108, v108
	v_fmac_f32_e32 v188, v109, v109
	v_fmac_f32_e32 v188, v110, v110
	v_fmac_f32_e32 v188, v111, v111
	v_fmac_f32_e32 v188, v112, v112
	v_fmac_f32_e32 v188, v113, v113
	v_fmac_f32_e32 v188, v114, v114
	v_fmac_f32_e32 v188, v115, v115
	v_fmac_f32_e32 v188, v116, v116
	v_fmac_f32_e32 v188, v117, v117
	s_waitcnt vmcnt(0)
	v_mul_f32_e32 v189, v118, v118
	v_fmac_f32_e32 v189, v119, v119
	v_fmac_f32_e32 v189, v120, v120
	v_fmac_f32_e32 v189, v121, v121
	v_fmac_f32_e32 v189, v122, v122
	v_fmac_f32_e32 v189, v123, v123
	v_fmac_f32_e32 v189, v124, v124
	v_fmac_f32_e32 v189, v125, v125
	v_fmac_f32_e32 v189, v126, v126
	v_fmac_f32_e32 v189, v127, v127
	v_fmac_f32_e32 v189, v128, v128
	v_fmac_f32_e32 v189, v129, v129
	v_fmac_f32_e32 v189, v130, v130
	v_fmac_f32_e32 v189, v131, v131
	v_fmac_f32_e32 v189, v132, v132
	v_fmac_f32_e32 v189, v133, v133
	s_nop 1
	v_add_f32_dpp v186, v186, v186 row_ror:8 row_mask:0xf bank_mask:0xf
	v_add_f32_dpp v187, v187, v187 row_ror:8 row_mask:0xf bank_mask:0xf
	v_add_f32_dpp v188, v188, v188 row_ror:8 row_mask:0xf bank_mask:0xf
	v_add_f32_dpp v189, v189, v189 row_ror:8 row_mask:0xf bank_mask:0xf
	v_add_f32_dpp v186, v186, v186 row_ror:4 row_mask:0xf bank_mask:0xf
	v_add_f32_dpp v187, v187, v187 row_ror:4 row_mask:0xf bank_mask:0xf
	v_add_f32_dpp v188, v188, v188 row_ror:4 row_mask:0xf bank_mask:0xf
	v_add_f32_dpp v189, v189, v189 row_ror:4 row_mask:0xf bank_mask:0xf
	v_add_f32_dpp v186, v186, v186 row_ror:2 row_mask:0xf bank_mask:0xf
	v_add_f32_dpp v187, v187, v187 row_ror:2 row_mask:0xf bank_mask:0xf
	v_add_f32_dpp v188, v188, v188 row_ror:2 row_mask:0xf bank_mask:0xf
	v_add_f32_dpp v189, v189, v189 row_ror:2 row_mask:0xf bank_mask:0xf
	v_add_f32_dpp v186, v186, v186 row_ror:1 row_mask:0xf bank_mask:0xf
	v_add_f32_dpp v187, v187, v187 row_ror:1 row_mask:0xf bank_mask:0xf
	v_add_f32_dpp v188, v188, v188 row_ror:1 row_mask:0xf bank_mask:0xf
	v_add_f32_dpp v189, v189, v189 row_ror:1 row_mask:0xf bank_mask:0xf
	v_mov_b32_e32 v190, v186
	v_mov_b32_e32 v191, v187
	v_mov_b32_e32 v192, v188
	v_mov_b32_e32 v193, v189
	s_nop 1
	v_permlane16_swap_b32_e32 v190, v186
	v_permlane16_swap_b32_e32 v191, v187
	v_permlane16_swap_b32_e32 v192, v188
	v_permlane16_swap_b32_e32 v193, v189
	v_add_f32_e32 v186, v186, v190
	v_add_f32_e32 v187, v187, v191
	v_add_f32_e32 v188, v188, v192
	v_add_f32_e32 v189, v189, v193
	v_mov_b32_e32 v190, v186
	v_mov_b32_e32 v191, v187
	v_mov_b32_e32 v192, v188
	v_mov_b32_e32 v193, v189
	s_nop 1
	v_permlane32_swap_b32_e32 v190, v186
	v_permlane32_swap_b32_e32 v191, v187
	v_permlane32_swap_b32_e32 v192, v188
	v_permlane32_swap_b32_e32 v193, v189
	v_add_f32_e32 v186, v186, v190
	v_add_f32_e32 v187, v187, v191
	v_add_f32_e32 v188, v188, v192
	v_add_f32_e32 v189, v189, v193
	v_fma_f32 v186, v186, s3, v167
	v_fma_f32 v187, v187, s3, v167
	v_fma_f32 v188, v188, s3, v167
	v_fma_f32 v189, v189, s3, v167
	v_rsq_f32_e32 v186, v186
	v_rsq_f32_e32 v187, v187
	v_rsq_f32_e32 v188, v188
	v_rsq_f32_e32 v189, v189
	s_nop 0
	v_mul_f32_e32 v70, v70, v186
	v_mul_f32_e32 v71, v71, v186
	v_mul_f32_e32 v72, v72, v186
	v_mul_f32_e32 v73, v73, v186
	v_mul_f32_e32 v74, v74, v186
	v_mul_f32_e32 v75, v75, v186
	v_mul_f32_e32 v76, v76, v186
	v_mul_f32_e32 v77, v77, v186
	v_mul_f32_e32 v78, v78, v186
	v_mul_f32_e32 v79, v79, v186
	v_mul_f32_e32 v80, v80, v186
	v_mul_f32_e32 v81, v81, v186
	v_mul_f32_e32 v82, v82, v186
	v_mul_f32_e32 v83, v83, v186
	v_mul_f32_e32 v84, v84, v186
	v_mul_f32_e32 v85, v85, v186
	v_fma_f32 v70, v70, v150, v170
	v_fma_f32 v71, v71, v151, v171
	v_fma_f32 v72, v72, v152, v172
	v_fma_f32 v73, v73, v153, v173
	v_fma_f32 v74, v74, v154, v174
	v_fma_f32 v75, v75, v155, v175
	v_fma_f32 v76, v76, v156, v176
	v_fma_f32 v77, v77, v157, v177
	v_fma_f32 v78, v78, v158, v178
	v_fma_f32 v79, v79, v159, v179
	v_fma_f32 v80, v80, v160, v180
	v_fma_f32 v81, v81, v161, v181
	v_fma_f32 v82, v82, v162, v182
	v_fma_f32 v83, v83, v163, v183
	v_fma_f32 v84, v84, v164, v184
	v_fma_f32 v85, v85, v165, v185
	v_cvt_pk_bf16_f32 v70, v70, v71
	v_cvt_pk_bf16_f32 v71, v72, v73
	v_cvt_pk_bf16_f32 v72, v74, v75
	v_cvt_pk_bf16_f32 v73, v76, v77
	v_cvt_pk_bf16_f32 v78, v78, v79
	v_cvt_pk_bf16_f32 v79, v80, v81
	v_cvt_pk_bf16_f32 v80, v82, v83
	v_cvt_pk_bf16_f32 v81, v84, v85
	ds_write_b64 v202, v[70:71] offset:8224
	ds_write_b64 v202, v[72:73] offset:8232
	ds_write_b64 v202, v[78:79] offset:9248
	ds_write_b64 v202, v[80:81] offset:9256
	v_mul_f32_e32 v86, v86, v187
	v_mul_f32_e32 v87, v87, v187
	v_mul_f32_e32 v88, v88, v187
	v_mul_f32_e32 v89, v89, v187
	v_mul_f32_e32 v90, v90, v187
	v_mul_f32_e32 v91, v91, v187
	v_mul_f32_e32 v92, v92, v187
	v_mul_f32_e32 v93, v93, v187
	v_mul_f32_e32 v94, v94, v187
	v_mul_f32_e32 v95, v95, v187
	v_mul_f32_e32 v96, v96, v187
	v_mul_f32_e32 v97, v97, v187
	v_mul_f32_e32 v98, v98, v187
	v_mul_f32_e32 v99, v99, v187
	v_mul_f32_e32 v100, v100, v187
	v_mul_f32_e32 v101, v101, v187
	v_fma_f32 v86, v86, v150, v170
	v_fma_f32 v87, v87, v151, v171
	v_fma_f32 v88, v88, v152, v172
	v_fma_f32 v89, v89, v153, v173
	v_fma_f32 v90, v90, v154, v174
	v_fma_f32 v91, v91, v155, v175
	v_fma_f32 v92, v92, v156, v176
	v_fma_f32 v93, v93, v157, v177
	v_fma_f32 v94, v94, v158, v178
	v_fma_f32 v95, v95, v159, v179
	v_fma_f32 v96, v96, v160, v180
	v_fma_f32 v97, v97, v161, v181
	v_fma_f32 v98, v98, v162, v182
	v_fma_f32 v99, v99, v163, v183
	v_fma_f32 v100, v100, v164, v184
	v_fma_f32 v101, v101, v165, v185
	v_cvt_pk_bf16_f32 v86, v86, v87
	v_cvt_pk_bf16_f32 v87, v88, v89
	v_cvt_pk_bf16_f32 v88, v90, v91
	v_cvt_pk_bf16_f32 v89, v92, v93
	v_cvt_pk_bf16_f32 v94, v94, v95
	v_cvt_pk_bf16_f32 v95, v96, v97
	v_cvt_pk_bf16_f32 v96, v98, v99
	v_cvt_pk_bf16_f32 v97, v100, v101
	ds_write_b64 v202, v[86:87] offset:10280
	ds_write_b64 v202, v[88:89] offset:10288
	ds_write_b64 v202, v[94:95] offset:11304
	ds_write_b64 v202, v[96:97] offset:11312
	v_mul_f32_e32 v102, v102, v188
	v_mul_f32_e32 v103, v103, v188
	v_mul_f32_e32 v104, v104, v188
	v_mul_f32_e32 v105, v105, v188
	v_mul_f32_e32 v106, v106, v188
	v_mul_f32_e32 v107, v107, v188
	v_mul_f32_e32 v108, v108, v188
	v_mul_f32_e32 v109, v109, v188
	v_mul_f32_e32 v110, v110, v188
	v_mul_f32_e32 v111, v111, v188
	v_mul_f32_e32 v112, v112, v188
	v_mul_f32_e32 v113, v113, v188
	v_mul_f32_e32 v114, v114, v188
	v_mul_f32_e32 v115, v115, v188
	v_mul_f32_e32 v116, v116, v188
	v_mul_f32_e32 v117, v117, v188
	v_fma_f32 v102, v102, v150, v170
	v_fma_f32 v103, v103, v151, v171
	v_fma_f32 v104, v104, v152, v172
	v_fma_f32 v105, v105, v153, v173
	v_fma_f32 v106, v106, v154, v174
	v_fma_f32 v107, v107, v155, v175
	v_fma_f32 v108, v108, v156, v176
	v_fma_f32 v109, v109, v157, v177
	v_fma_f32 v110, v110, v158, v178
	v_fma_f32 v111, v111, v159, v179
	v_fma_f32 v112, v112, v160, v180
	v_fma_f32 v113, v113, v161, v181
	v_fma_f32 v114, v114, v162, v182
	v_fma_f32 v115, v115, v163, v183
	v_fma_f32 v116, v116, v164, v184
	v_fma_f32 v117, v117, v165, v185
	v_cvt_pk_bf16_f32 v102, v102, v103
	v_cvt_pk_bf16_f32 v103, v104, v105
	v_cvt_pk_bf16_f32 v104, v106, v107
	v_cvt_pk_bf16_f32 v105, v108, v109
	v_cvt_pk_bf16_f32 v110, v110, v111
	v_cvt_pk_bf16_f32 v111, v112, v113
	v_cvt_pk_bf16_f32 v112, v114, v115
	v_cvt_pk_bf16_f32 v113, v116, v117
	ds_write_b64 v202, v[102:103] offset:12336
	ds_write_b64 v202, v[104:105] offset:12344
	ds_write_b64 v202, v[110:111] offset:13360
	ds_write_b64 v202, v[112:113] offset:13368
	v_mul_f32_e32 v118, v118, v189
	v_mul_f32_e32 v119, v119, v189
	v_mul_f32_e32 v120, v120, v189
	v_mul_f32_e32 v121, v121, v189
	v_mul_f32_e32 v122, v122, v189
	v_mul_f32_e32 v123, v123, v189
	v_mul_f32_e32 v124, v124, v189
	v_mul_f32_e32 v125, v125, v189
	v_mul_f32_e32 v126, v126, v189
	v_mul_f32_e32 v127, v127, v189
	v_mul_f32_e32 v128, v128, v189
	v_mul_f32_e32 v129, v129, v189
	v_mul_f32_e32 v130, v130, v189
	v_mul_f32_e32 v131, v131, v189
	v_mul_f32_e32 v132, v132, v189
	v_mul_f32_e32 v133, v133, v189
	v_fma_f32 v118, v118, v150, v170
	v_fma_f32 v119, v119, v151, v171
	v_fma_f32 v120, v120, v152, v172
	v_fma_f32 v121, v121, v153, v173
	v_fma_f32 v122, v122, v154, v174
	v_fma_f32 v123, v123, v155, v175
	v_fma_f32 v124, v124, v156, v176
	v_fma_f32 v125, v125, v157, v177
	v_fma_f32 v126, v126, v158, v178
	v_fma_f32 v127, v127, v159, v179
	v_fma_f32 v128, v128, v160, v180
	v_fma_f32 v129, v129, v161, v181
	v_fma_f32 v130, v130, v162, v182
	v_fma_f32 v131, v131, v163, v183
	v_fma_f32 v132, v132, v164, v184
	v_fma_f32 v133, v133, v165, v185
	v_cvt_pk_bf16_f32 v118, v118, v119
	v_cvt_pk_bf16_f32 v119, v120, v121
	v_cvt_pk_bf16_f32 v120, v122, v123
	v_cvt_pk_bf16_f32 v121, v124, v125
	v_cvt_pk_bf16_f32 v126, v126, v127
	v_cvt_pk_bf16_f32 v127, v128, v129
	v_cvt_pk_bf16_f32 v128, v130, v131
	v_cvt_pk_bf16_f32 v129, v132, v133
	ds_write_b64 v202, v[118:119] offset:14392
	ds_write_b64 v202, v[120:121] offset:14400
	ds_write_b64 v202, v[126:127] offset:15416
	ds_write_b64 v202, v[128:129] offset:15424
	s_waitcnt lgkmcnt(0)
	s_barrier
	v_mbcnt_lo_u32_b32 v91, -1, 0
	v_mbcnt_hi_u32_b32 v91, -1, v91
	v_readlane_b32 s9, v254, 63
	v_and_b32_e32 v88, 7, v91
	v_lshrrev_b32_e32 v89, 3, v91
	v_lshl_add_u32 v89, s9, 3, v89
	v_mul_u32_u24_e32 v90, 16448, v88
	v_lshl_add_u32 v90, v89, 2, v90
	v_mul_u32_u24_e32 v89, 0xc000, v89
	v_lshl_add_u32 v89, v88, 4, v89
	v_add_u32_e32 v88, 0x6000, v89
	s_lshl_b32 s8, s7, 7
	v_readlane_b32 s10, v255, 7
	v_readlane_b32 s11, v255, 8
	s_add_u32 s10, s10, 0xd000000
	s_addc_u32 s11, s11, 0
	s_add_u32 s10, s10, s8
	s_addc_u32 s11, s11, 0
	s_mov_b32 s1, 0x5040100
	s_mov_b32 s3, 0x7060302
	ds_read_b32 v70, v90 offset:0
	ds_read_b32 v71, v90 offset:2056
	ds_read_b32 v72, v90 offset:4112
	ds_read_b32 v73, v90 offset:6168
	ds_read_b32 v74, v90 offset:8224
	ds_read_b32 v75, v90 offset:10280
	ds_read_b32 v76, v90 offset:12336
	ds_read_b32 v77, v90 offset:14392
	ds_read_b32 v92, v90 offset:256
	ds_read_b32 v93, v90 offset:2312
	ds_read_b32 v94, v90 offset:4368
	ds_read_b32 v95, v90 offset:6424
	ds_read_b32 v96, v90 offset:8480
	ds_read_b32 v97, v90 offset:10536
	ds_read_b32 v98, v90 offset:12592
	ds_read_b32 v99, v90 offset:14648
	s_waitcnt lgkmcnt(8)
	v_perm_b32 v80, v71, v70, s1
	v_perm_b32 v81, v73, v72, s1
	v_perm_b32 v82, v75, v74, s1
	v_perm_b32 v83, v77, v76, s1
	v_perm_b32 v84, v71, v70, s3
	v_perm_b32 v85, v73, v72, s3
	v_perm_b32 v86, v75, v74, s3
	v_perm_b32 v87, v77, v76, s3
	global_store_dwordx4 v89, v[80:83], s[10:11] sc1
	global_store_dwordx4 v88, v[84:87], s[10:11] sc1
	s_add_u32 s10, s10, 0x300000
	s_addc_u32 s11, s11, 0
	ds_read_b32 v70, v90 offset:512
	ds_read_b32 v71, v90 offset:2568
	ds_read_b32 v72, v90 offset:4624
	ds_read_b32 v73, v90 offset:6680
	ds_read_b32 v74, v90 offset:8736
	ds_read_b32 v75, v90 offset:10792
	ds_read_b32 v76, v90 offset:12848
	ds_read_b32 v77, v90 offset:14904
	s_waitcnt lgkmcnt(8)
	v_perm_b32 v80, v93, v92, s1
	v_perm_b32 v81, v95, v94, s1
	v_perm_b32 v82, v97, v96, s1
	v_perm_b32 v83, v99, v98, s1
	v_perm_b32 v84, v93, v92, s3
	v_perm_b32 v85, v95, v94, s3
	v_perm_b32 v86, v97, v96, s3
	v_perm_b32 v87, v99, v98, s3
	global_store_dwordx4 v89, v[80:83], s[10:11] sc1
	global_store_dwordx4 v88, v[84:87], s[10:11] sc1
	s_add_u32 s10, s10, 0x300000
	s_addc_u32 s11, s11, 0
	ds_read_b32 v92, v90 offset:768
	ds_read_b32 v93, v90 offset:2824
	ds_read_b32 v94, v90 offset:4880
	ds_read_b32 v95, v90 offset:6936
	ds_read_b32 v96, v90 offset:8992
	ds_read_b32 v97, v90 offset:11048
	ds_read_b32 v98, v90 offset:13104
	ds_read_b32 v99, v90 offset:15160
	s_waitcnt lgkmcnt(8)
	v_perm_b32 v80, v71, v70, s1
	v_perm_b32 v81, v73, v72, s1
	v_perm_b32 v82, v75, v74, s1
	v_perm_b32 v83, v77, v76, s1
	v_perm_b32 v84, v71, v70, s3
	v_perm_b32 v85, v73, v72, s3
	v_perm_b32 v86, v75, v74, s3
	v_perm_b32 v87, v77, v76, s3
	global_store_dwordx4 v89, v[80:83], s[10:11] sc1
	global_store_dwordx4 v88, v[84:87], s[10:11] sc1
	s_add_u32 s10, s10, 0x300000
	s_addc_u32 s11, s11, 0
	ds_read_b32 v70, v90 offset:1024
	ds_read_b32 v71, v90 offset:3080
	ds_read_b32 v72, v90 offset:5136
	ds_read_b32 v73, v90 offset:7192
	ds_read_b32 v74, v90 offset:9248
	ds_read_b32 v75, v90 offset:11304
	ds_read_b32 v76, v90 offset:13360
	ds_read_b32 v77, v90 offset:15416
	s_waitcnt lgkmcnt(8)
	v_perm_b32 v80, v93, v92, s1
	v_perm_b32 v81, v95, v94, s1
	v_perm_b32 v82, v97, v96, s1
	v_perm_b32 v83, v99, v98, s1
	v_perm_b32 v84, v93, v92, s3
	v_perm_b32 v85, v95, v94, s3
	v_perm_b32 v86, v97, v96, s3
	v_perm_b32 v87, v99, v98, s3
	global_store_dwordx4 v89, v[80:83], s[10:11] sc1
	global_store_dwordx4 v88, v[84:87], s[10:11] sc1
	s_add_u32 s10, s10, 0x300000
	s_addc_u32 s11, s11, 0
	ds_read_b32 v92, v90 offset:1280
	ds_read_b32 v93, v90 offset:3336
	ds_read_b32 v94, v90 offset:5392
	ds_read_b32 v95, v90 offset:7448
	ds_read_b32 v96, v90 offset:9504
	ds_read_b32 v97, v90 offset:11560
	ds_read_b32 v98, v90 offset:13616
	ds_read_b32 v99, v90 offset:15672
	s_waitcnt lgkmcnt(8)
	v_perm_b32 v80, v71, v70, s1
	v_perm_b32 v81, v73, v72, s1
	v_perm_b32 v82, v75, v74, s1
	v_perm_b32 v83, v77, v76, s1
	v_perm_b32 v84, v71, v70, s3
	v_perm_b32 v85, v73, v72, s3
	v_perm_b32 v86, v75, v74, s3
	v_perm_b32 v87, v77, v76, s3
	global_store_dwordx4 v89, v[80:83], s[10:11] sc1
	global_store_dwordx4 v88, v[84:87], s[10:11] sc1
	s_add_u32 s10, s10, 0x300000
	s_addc_u32 s11, s11, 0
	ds_read_b32 v70, v90 offset:1536
	ds_read_b32 v71, v90 offset:3592
	ds_read_b32 v72, v90 offset:5648
	ds_read_b32 v73, v90 offset:7704
	ds_read_b32 v74, v90 offset:9760
	ds_read_b32 v75, v90 offset:11816
	ds_read_b32 v76, v90 offset:13872
	ds_read_b32 v77, v90 offset:15928
	s_waitcnt lgkmcnt(8)
	v_perm_b32 v80, v93, v92, s1
	v_perm_b32 v81, v95, v94, s1
	v_perm_b32 v82, v97, v96, s1
	v_perm_b32 v83, v99, v98, s1
	v_perm_b32 v84, v93, v92, s3
	v_perm_b32 v85, v95, v94, s3
	v_perm_b32 v86, v97, v96, s3
	v_perm_b32 v87, v99, v98, s3
	global_store_dwordx4 v89, v[80:83], s[10:11] sc1
	global_store_dwordx4 v88, v[84:87], s[10:11] sc1
	s_add_u32 s10, s10, 0x300000
	s_addc_u32 s11, s11, 0
	ds_read_b32 v92, v90 offset:1792
	ds_read_b32 v93, v90 offset:3848
	ds_read_b32 v94, v90 offset:5904
	ds_read_b32 v95, v90 offset:7960
	ds_read_b32 v96, v90 offset:10016
	ds_read_b32 v97, v90 offset:12072
	ds_read_b32 v98, v90 offset:14128
	ds_read_b32 v99, v90 offset:16184
	s_waitcnt lgkmcnt(8)
	v_perm_b32 v80, v71, v70, s1
	v_perm_b32 v81, v73, v72, s1
	v_perm_b32 v82, v75, v74, s1
	v_perm_b32 v83, v77, v76, s1
	v_perm_b32 v84, v71, v70, s3
	v_perm_b32 v85, v73, v72, s3
	v_perm_b32 v86, v75, v74, s3
	v_perm_b32 v87, v77, v76, s3
	global_store_dwordx4 v89, v[80:83], s[10:11] sc1
	global_store_dwordx4 v88, v[84:87], s[10:11] sc1
	s_add_u32 s10, s10, 0x300000
	s_addc_u32 s11, s11, 0
	s_waitcnt lgkmcnt(0)
	v_perm_b32 v80, v93, v92, s1
	v_perm_b32 v81, v95, v94, s1
	v_perm_b32 v82, v97, v96, s1
	v_perm_b32 v83, v99, v98, s1
	v_perm_b32 v84, v93, v92, s3
	v_perm_b32 v85, v95, v94, s3
	v_perm_b32 v86, v97, v96, s3
	v_perm_b32 v87, v99, v98, s3
	global_store_dwordx4 v89, v[80:83], s[10:11] sc1
	global_store_dwordx4 v88, v[84:87], s[10:11] sc1
	s_add_i32 s7, s7, s78
	s_add_i32 s2, s2, s35
	s_cmpk_gt_i32 s7, 0xbf
	s_barrier
	s_cbranch_scc0 .LBB0_896
